# v080 + GEMM K-loops: A-fragment LDS read addresses folded into ds_read offsets (one base register per loop), no VALU left in the load segments
# speedup vs baseline: 1.0080x; 1.0025x over previous
.LBB0_350:
	s_ashr_i32 s15, s14, 31
	s_lshl_b64 s[16:17], s[14:15], 20
	s_add_u32 s16, s20, s16
	s_addc_u32 s17, s41, s17
	s_and_b64 s[24:25], s[0:1], exec
	s_cselect_b32 s15, s17, s31
	s_cselect_b32 s62, s16, s30
	s_ashr_i32 s13, s12, 31
	s_lshl_b64 s[24:25], s[12:13], 20
	s_add_u32 s24, s42, s24
	s_addc_u32 s25, s43, s25
	s_and_b64 s[38:39], s[0:1], exec
	s_cselect_b32 s13, s25, s29
	s_cselect_b32 s63, s24, s28
	s_add_u32 s68, s28, 0x100
	s_addc_u32 s69, s29, 0
	s_add_u32 s28, s30, 0x80080
	v_mov_b32_e32 v2, 0
	s_addc_u32 s29, s31, 0
	s_mov_b32 s70, -2
	v_mov_b32_e32 v3, v2
	v_mov_b32_e32 v4, v2
	v_mov_b32_e32 v5, v2
	v_mov_b32_e32 v6, v2
	v_mov_b32_e32 v7, v2
	v_mov_b32_e32 v8, v2
	v_mov_b32_e32 v9, v2
	v_mov_b32_e32 v18, v2
	v_mov_b32_e32 v19, v2
	v_mov_b32_e32 v20, v2
	v_mov_b32_e32 v21, v2
	v_mov_b32_e32 v22, v2
	v_mov_b32_e32 v23, v2
	v_mov_b32_e32 v24, v2
	v_mov_b32_e32 v25, v2
	v_mov_b32_e32 v34, v2
	v_mov_b32_e32 v35, v2
	v_mov_b32_e32 v36, v2
	v_mov_b32_e32 v37, v2
	v_mov_b32_e32 v38, v2
	v_mov_b32_e32 v39, v2
	v_mov_b32_e32 v40, v2
	v_mov_b32_e32 v41, v2
	v_mov_b32_e32 v50, v2
	v_mov_b32_e32 v51, v2
	v_mov_b32_e32 v52, v2
	v_mov_b32_e32 v53, v2
	v_mov_b32_e32 v54, v2
	v_mov_b32_e32 v55, v2
	v_mov_b32_e32 v56, v2
	v_mov_b32_e32 v57, v2
	v_mov_b32_e32 v10, v2
	v_mov_b32_e32 v11, v2
	v_mov_b32_e32 v12, v2
	v_mov_b32_e32 v13, v2
	v_mov_b32_e32 v14, v2
	v_mov_b32_e32 v15, v2
	v_mov_b32_e32 v16, v2
	v_mov_b32_e32 v17, v2
	v_mov_b32_e32 v26, v2
	v_mov_b32_e32 v27, v2
	v_mov_b32_e32 v28, v2
	v_mov_b32_e32 v29, v2
	v_mov_b32_e32 v30, v2
	v_mov_b32_e32 v31, v2
	v_mov_b32_e32 v32, v2
	v_mov_b32_e32 v33, v2
	v_mov_b32_e32 v42, v2
	v_mov_b32_e32 v43, v2
	v_mov_b32_e32 v44, v2
	v_mov_b32_e32 v45, v2
	v_mov_b32_e32 v46, v2
	v_mov_b32_e32 v47, v2
	v_mov_b32_e32 v48, v2
	v_mov_b32_e32 v49, v2
	v_mov_b32_e32 v58, v2
	v_mov_b32_e32 v59, v2
	v_mov_b32_e32 v60, v2
	v_mov_b32_e32 v61, v2
	v_mov_b32_e32 v62, v2
	v_mov_b32_e32 v63, v2
	v_mov_b32_e32 v64, v2
	v_mov_b32_e32 v65, v2
	v_mov_b32_e32 v66, v2
	v_mov_b32_e32 v67, v2
	v_mov_b32_e32 v68, v2
	v_mov_b32_e32 v69, v2
	v_mov_b32_e32 v70, v2
	v_mov_b32_e32 v71, v2
	v_mov_b32_e32 v72, v2
	v_mov_b32_e32 v73, v2
	v_mov_b32_e32 v82, v2
	v_mov_b32_e32 v83, v2
	v_mov_b32_e32 v84, v2
	v_mov_b32_e32 v85, v2
	v_mov_b32_e32 v86, v2
	v_mov_b32_e32 v87, v2
	v_mov_b32_e32 v88, v2
	v_mov_b32_e32 v89, v2
	v_mov_b32_e32 v98, v2
	v_mov_b32_e32 v99, v2
	v_mov_b32_e32 v100, v2
	v_mov_b32_e32 v101, v2
	v_mov_b32_e32 v102, v2
	v_mov_b32_e32 v103, v2
	v_mov_b32_e32 v104, v2
	v_mov_b32_e32 v105, v2
	v_mov_b32_e32 v114, v2
	v_mov_b32_e32 v115, v2
	v_mov_b32_e32 v116, v2
	v_mov_b32_e32 v117, v2
	v_mov_b32_e32 v118, v2
	v_mov_b32_e32 v119, v2
	v_mov_b32_e32 v120, v2
	v_mov_b32_e32 v121, v2
	v_mov_b32_e32 v74, v2
	v_mov_b32_e32 v75, v2
	v_mov_b32_e32 v76, v2
	v_mov_b32_e32 v77, v2
	v_mov_b32_e32 v78, v2
	v_mov_b32_e32 v79, v2
	v_mov_b32_e32 v80, v2
	v_mov_b32_e32 v81, v2
	v_mov_b32_e32 v90, v2
	v_mov_b32_e32 v91, v2
	v_mov_b32_e32 v92, v2
	v_mov_b32_e32 v93, v2
	v_mov_b32_e32 v94, v2
	v_mov_b32_e32 v95, v2
	v_mov_b32_e32 v96, v2
	v_mov_b32_e32 v97, v2
	v_mov_b32_e32 v106, v2
	v_mov_b32_e32 v107, v2
	v_mov_b32_e32 v108, v2
	v_mov_b32_e32 v109, v2
	v_mov_b32_e32 v110, v2
	v_mov_b32_e32 v111, v2
	v_mov_b32_e32 v112, v2
	v_mov_b32_e32 v113, v2
	v_mov_b32_e32 v122, v2
	v_mov_b32_e32 v123, v2
	v_mov_b32_e32 v124, v2
	v_mov_b32_e32 v125, v2
	v_mov_b32_e32 v126, v2
	v_mov_b32_e32 v127, v2
	v_mov_b32_e32 v128, v2
	v_mov_b32_e32 v129, v2
	v_add_u32_e32 v212, 0x10000, v151
.LBB0_351:
	s_add_u32 s30, s28, 0xfff80080
	s_addc_u32 s31, s29, -1
	s_add_i32 s71, 0, 0x10000
	s_cmp_eq_u32 s70, 28
	s_cselect_b32 s39, s15, s31
	s_cselect_b32 s38, s62, s30
	s_cselect_b32 s31, s13, s69
	s_cselect_b32 s30, s63, s68
	s_add_i32 s74, 0, 0x14000
	ds_read_b128 v[142:145], v212
	ds_read_b128 v[146:149], v212 offset:1024
	ds_read_b128 v[154:157], v212 offset:2048
	ds_read_b128 v[158:161], v212 offset:3072
	ds_read_b128 v[162:165], v212 offset:16384
	ds_read_b128 v[166:169], v212 offset:17408
	ds_read_b128 v[176:179], v212 offset:18432
	ds_read_b128 v[180:183], v212 offset:19456
	s_add_i32 m0, s45, 0xc000
	ds_read_b128 v[184:187], v153
	ds_read_b128 v[188:191], v153 offset:1024
	ds_read_b128 v[192:195], v153 offset:2048
	ds_read_b128 v[196:199], v153 offset:3072
	ds_read_b128 v[208:211], v153 offset:4096
	ds_read_b128 v[222:225], v153 offset:5120
	ds_read_b128 v[226:229], v153 offset:6144
	ds_read_b128 v[230:233], v153 offset:7168
	global_load_lds_dwordx4 v140, s[28:29]
	s_add_i32 m0, s45, 0xe000
	s_nop 0
	global_load_lds_dwordx4 v138, s[28:29]
	s_waitcnt vmcnt(8)
	s_waitcnt lgkmcnt(0)
	s_barrier
	s_setprio 1
	s_waitcnt lgkmcnt(0)
	v_mfma_f32_16x16x32_bf16 v[126:129], v[142:145], v[184:187], v[126:129]
	v_mfma_f32_16x16x32_bf16 v[122:125], v[154:157], v[184:187], v[122:125]
	v_mfma_f32_16x16x32_bf16 v[110:113], v[142:145], v[192:195], v[110:113]
	v_mfma_f32_16x16x32_bf16 v[106:109], v[154:157], v[192:195], v[106:109]
	v_mfma_f32_16x16x32_bf16 v[94:97], v[142:145], v[208:211], v[94:97]
	v_mfma_f32_16x16x32_bf16 v[90:93], v[154:157], v[208:211], v[90:93]
	v_mfma_f32_16x16x32_bf16 v[78:81], v[142:145], v[226:229], v[78:81]
	v_mfma_f32_16x16x32_bf16 v[74:77], v[154:157], v[226:229], v[74:77]
	v_mfma_f32_16x16x32_bf16 v[126:129], v[146:149], v[188:191], v[126:129]
	v_mfma_f32_16x16x32_bf16 v[122:125], v[158:161], v[188:191], v[122:125]
	v_mfma_f32_16x16x32_bf16 v[110:113], v[146:149], v[196:199], v[110:113]
	v_mfma_f32_16x16x32_bf16 v[106:109], v[158:161], v[196:199], v[106:109]
	v_mfma_f32_16x16x32_bf16 v[94:97], v[146:149], v[222:225], v[94:97]
	v_mfma_f32_16x16x32_bf16 v[90:93], v[158:161], v[222:225], v[90:93]
	v_mfma_f32_16x16x32_bf16 v[78:81], v[146:149], v[230:233], v[78:81]
	v_mfma_f32_16x16x32_bf16 v[74:77], v[158:161], v[230:233], v[74:77]
	s_setprio 0
	s_setprio 1
	v_mfma_f32_16x16x32_bf16 v[118:121], v[162:165], v[184:187], v[118:121]
	v_mfma_f32_16x16x32_bf16 v[114:117], v[176:179], v[184:187], v[114:117]
	v_mfma_f32_16x16x32_bf16 v[102:105], v[162:165], v[192:195], v[102:105]
	v_mfma_f32_16x16x32_bf16 v[98:101], v[176:179], v[192:195], v[98:101]
	v_mfma_f32_16x16x32_bf16 v[86:89], v[162:165], v[208:211], v[86:89]
	v_mfma_f32_16x16x32_bf16 v[82:85], v[176:179], v[208:211], v[82:85]
	v_mfma_f32_16x16x32_bf16 v[70:73], v[162:165], v[226:229], v[70:73]
	v_mfma_f32_16x16x32_bf16 v[66:69], v[176:179], v[226:229], v[66:69]
	v_mfma_f32_16x16x32_bf16 v[118:121], v[166:169], v[188:191], v[118:121]
	v_mfma_f32_16x16x32_bf16 v[114:117], v[180:183], v[188:191], v[114:117]
	v_mfma_f32_16x16x32_bf16 v[102:105], v[166:169], v[196:199], v[102:105]
	v_mfma_f32_16x16x32_bf16 v[98:101], v[180:183], v[196:199], v[98:101]
	v_mfma_f32_16x16x32_bf16 v[86:89], v[166:169], v[222:225], v[86:89]
	v_mfma_f32_16x16x32_bf16 v[82:85], v[180:183], v[222:225], v[82:85]
	v_mfma_f32_16x16x32_bf16 v[70:73], v[166:169], v[230:233], v[70:73]
	v_mfma_f32_16x16x32_bf16 v[66:69], v[180:183], v[230:233], v[66:69]
	s_setprio 0
	s_barrier
	s_add_i32 s71, s71, s44
	s_add_u32 s98, s30, s34
	s_addc_u32 s99, s31, s35
	s_mov_b32 m0, s71
	ds_read_b128 v[184:187], v153 offset:16384
	ds_read_b128 v[188:191], v153 offset:17408
	ds_read_b128 v[192:195], v153 offset:18432
	ds_read_b128 v[196:199], v153 offset:19456
	ds_read_b128 v[208:211], v153 offset:20480
	ds_read_b128 v[222:225], v153 offset:21504
	ds_read_b128 v[226:229], v153 offset:22528
	ds_read_b128 v[230:233], v153 offset:23552
	global_load_lds_dwordx4 v130, s[30:31]
	s_add_i32 m0, s71, 0x2000
	s_add_u32 s72, s30, 0x80000
	s_addc_u32 s73, s31, 0
	s_add_i32 s71, s74, s44
	global_load_lds_dwordx4 v132, s[30:31]
	s_mov_b32 m0, s71
	s_nop 0
	global_load_lds_dwordx4 v130, s[72:73]
	s_add_i32 m0, s71, 0x2000
	s_nop 0
	global_load_lds_dwordx4 v132, s[72:73]
	s_add_u32 s100, s38, s34
	s_addc_u32 s101, s39, s35
	s_mov_b32 m0, s45
	s_nop 0
	global_load_lds_dwordx4 v136, s[38:39]
	s_mov_b32 m0, s46
	s_nop 0
	global_load_lds_dwordx4 v134, s[38:39]
	s_waitcnt vmcnt(8)
	s_waitcnt lgkmcnt(0)
	s_barrier
	s_setprio 1
	s_waitcnt lgkmcnt(0)
	v_mfma_f32_16x16x32_bf16 v[62:65], v[142:145], v[184:187], v[62:65]
	v_mfma_f32_16x16x32_bf16 v[58:61], v[154:157], v[184:187], v[58:61]
	v_mfma_f32_16x16x32_bf16 v[46:49], v[142:145], v[192:195], v[46:49]
	v_mfma_f32_16x16x32_bf16 v[42:45], v[154:157], v[192:195], v[42:45]
	v_mfma_f32_16x16x32_bf16 v[30:33], v[142:145], v[208:211], v[30:33]
	v_mfma_f32_16x16x32_bf16 v[26:29], v[154:157], v[208:211], v[26:29]
	v_mfma_f32_16x16x32_bf16 v[14:17], v[142:145], v[226:229], v[14:17]
	v_mfma_f32_16x16x32_bf16 v[10:13], v[154:157], v[226:229], v[10:13]
	v_mfma_f32_16x16x32_bf16 v[62:65], v[146:149], v[188:191], v[62:65]
	v_mfma_f32_16x16x32_bf16 v[58:61], v[158:161], v[188:191], v[58:61]
	v_mfma_f32_16x16x32_bf16 v[46:49], v[146:149], v[196:199], v[46:49]
	v_mfma_f32_16x16x32_bf16 v[42:45], v[158:161], v[196:199], v[42:45]
	v_mfma_f32_16x16x32_bf16 v[30:33], v[146:149], v[222:225], v[30:33]
	v_mfma_f32_16x16x32_bf16 v[26:29], v[158:161], v[222:225], v[26:29]
	v_mfma_f32_16x16x32_bf16 v[14:17], v[146:149], v[230:233], v[14:17]
	v_mfma_f32_16x16x32_bf16 v[10:13], v[158:161], v[230:233], v[10:13]
	s_setprio 0
	s_setprio 1
	v_mfma_f32_16x16x32_bf16 v[54:57], v[162:165], v[184:187], v[54:57]
	v_mfma_f32_16x16x32_bf16 v[50:53], v[176:179], v[184:187], v[50:53]
	v_mfma_f32_16x16x32_bf16 v[38:41], v[162:165], v[192:195], v[38:41]
	v_mfma_f32_16x16x32_bf16 v[34:37], v[176:179], v[192:195], v[34:37]
	v_mfma_f32_16x16x32_bf16 v[22:25], v[162:165], v[208:211], v[22:25]
	v_mfma_f32_16x16x32_bf16 v[18:21], v[176:179], v[208:211], v[18:21]
	v_mfma_f32_16x16x32_bf16 v[6:9], v[162:165], v[226:229], v[6:9]
	v_mfma_f32_16x16x32_bf16 v[2:5], v[176:179], v[226:229], v[2:5]
	v_mfma_f32_16x16x32_bf16 v[54:57], v[166:169], v[188:191], v[54:57]
	v_mfma_f32_16x16x32_bf16 v[50:53], v[180:183], v[188:191], v[50:53]
	v_mfma_f32_16x16x32_bf16 v[38:41], v[166:169], v[196:199], v[38:41]
	v_mfma_f32_16x16x32_bf16 v[34:37], v[180:183], v[196:199], v[34:37]
	v_mfma_f32_16x16x32_bf16 v[22:25], v[166:169], v[222:225], v[22:25]
	v_mfma_f32_16x16x32_bf16 v[18:21], v[180:183], v[222:225], v[18:21]
	v_mfma_f32_16x16x32_bf16 v[6:9], v[166:169], v[230:233], v[6:9]
	v_mfma_f32_16x16x32_bf16 v[2:5], v[180:183], v[230:233], v[2:5]
	s_setprio 0
	s_barrier
	s_add_i32 s71, 0, 0x18000
	s_add_i32 s72, 0, 0x1c000
	ds_read_b128 v[142:145], v212 offset:32768
	ds_read_b128 v[146:149], v212 offset:33792
	ds_read_b128 v[154:157], v212 offset:34816
	ds_read_b128 v[158:161], v212 offset:35840
	ds_read_b128 v[162:165], v212 offset:49152
	ds_read_b128 v[166:169], v212 offset:50176
	ds_read_b128 v[176:179], v212 offset:51200
	ds_read_b128 v[180:183], v212 offset:52224
	s_add_u32 s38, s38, 0x80000
	s_addc_u32 s39, s39, 0
	s_mov_b32 m0, s47
	ds_read_b128 v[184:187], v153 offset:32768
	ds_read_b128 v[188:191], v153 offset:33792
	ds_read_b128 v[192:195], v153 offset:34816
	ds_read_b128 v[196:199], v153 offset:35840
	ds_read_b128 v[208:211], v153 offset:36864
	ds_read_b128 v[222:225], v153 offset:37888
	ds_read_b128 v[226:229], v153 offset:38912
	ds_read_b128 v[230:233], v153 offset:39936
	global_load_lds_dwordx4 v136, s[38:39]
	s_mov_b32 m0, s48
	s_nop 0
	global_load_lds_dwordx4 v134, s[38:39]
	s_waitcnt vmcnt(8)
	s_waitcnt lgkmcnt(0)
	s_barrier
	s_setprio 1
	s_waitcnt lgkmcnt(0)
	v_mfma_f32_16x16x32_bf16 v[126:129], v[142:145], v[184:187], v[126:129]
	v_mfma_f32_16x16x32_bf16 v[122:125], v[154:157], v[184:187], v[122:125]
	v_mfma_f32_16x16x32_bf16 v[110:113], v[142:145], v[192:195], v[110:113]
	v_mfma_f32_16x16x32_bf16 v[106:109], v[154:157], v[192:195], v[106:109]
	v_mfma_f32_16x16x32_bf16 v[94:97], v[142:145], v[208:211], v[94:97]
	v_mfma_f32_16x16x32_bf16 v[90:93], v[154:157], v[208:211], v[90:93]
	v_mfma_f32_16x16x32_bf16 v[78:81], v[142:145], v[226:229], v[78:81]
	v_mfma_f32_16x16x32_bf16 v[74:77], v[154:157], v[226:229], v[74:77]
	v_mfma_f32_16x16x32_bf16 v[126:129], v[146:149], v[188:191], v[126:129]
	v_mfma_f32_16x16x32_bf16 v[122:125], v[158:161], v[188:191], v[122:125]
	v_mfma_f32_16x16x32_bf16 v[110:113], v[146:149], v[196:199], v[110:113]
	v_mfma_f32_16x16x32_bf16 v[106:109], v[158:161], v[196:199], v[106:109]
	v_mfma_f32_16x16x32_bf16 v[94:97], v[146:149], v[222:225], v[94:97]
	v_mfma_f32_16x16x32_bf16 v[90:93], v[158:161], v[222:225], v[90:93]
	v_mfma_f32_16x16x32_bf16 v[78:81], v[146:149], v[230:233], v[78:81]
	v_mfma_f32_16x16x32_bf16 v[74:77], v[158:161], v[230:233], v[74:77]
	s_setprio 0
	s_setprio 1
	v_mfma_f32_16x16x32_bf16 v[118:121], v[162:165], v[184:187], v[118:121]
	v_mfma_f32_16x16x32_bf16 v[114:117], v[176:179], v[184:187], v[114:117]
	v_mfma_f32_16x16x32_bf16 v[102:105], v[162:165], v[192:195], v[102:105]
	v_mfma_f32_16x16x32_bf16 v[98:101], v[176:179], v[192:195], v[98:101]
	v_mfma_f32_16x16x32_bf16 v[86:89], v[162:165], v[208:211], v[86:89]
	v_mfma_f32_16x16x32_bf16 v[82:85], v[176:179], v[208:211], v[82:85]
	v_mfma_f32_16x16x32_bf16 v[70:73], v[162:165], v[226:229], v[70:73]
	v_mfma_f32_16x16x32_bf16 v[66:69], v[176:179], v[226:229], v[66:69]
	v_mfma_f32_16x16x32_bf16 v[118:121], v[166:169], v[188:191], v[118:121]
	v_mfma_f32_16x16x32_bf16 v[114:117], v[180:183], v[188:191], v[114:117]
	v_mfma_f32_16x16x32_bf16 v[102:105], v[166:169], v[196:199], v[102:105]
	v_mfma_f32_16x16x32_bf16 v[98:101], v[180:183], v[196:199], v[98:101]
	v_mfma_f32_16x16x32_bf16 v[86:89], v[166:169], v[222:225], v[86:89]
	v_mfma_f32_16x16x32_bf16 v[82:85], v[180:183], v[222:225], v[82:85]
	v_mfma_f32_16x16x32_bf16 v[70:73], v[166:169], v[230:233], v[70:73]
	v_mfma_f32_16x16x32_bf16 v[66:69], v[180:183], v[230:233], v[66:69]
	s_setprio 0
	s_barrier
	s_add_i32 s38, s71, s44
	s_mov_b32 m0, s38
	ds_read_b128 v[184:187], v153 offset:49152
	ds_read_b128 v[188:191], v153 offset:50176
	ds_read_b128 v[192:195], v153 offset:51200
	ds_read_b128 v[196:199], v153 offset:52224
	ds_read_b128 v[208:211], v153 offset:53248
	ds_read_b128 v[222:225], v153 offset:54272
	ds_read_b128 v[226:229], v153 offset:55296
	ds_read_b128 v[230:233], v153 offset:56320
	global_load_lds_dwordx4 v130, s[98:99]
	s_add_i32 m0, s38, 0x2000
	s_add_u32 s30, s30, 0x80080
	s_addc_u32 s31, s31, 0
	s_add_i32 s38, s72, s44
	global_load_lds_dwordx4 v132, s[98:99]
	s_mov_b32 m0, s38
	s_nop 0
	global_load_lds_dwordx4 v130, s[30:31]
	s_add_i32 m0, s38, 0x2000
	s_nop 0
	global_load_lds_dwordx4 v132, s[30:31]
	s_mov_b32 m0, s57
	s_nop 0
	global_load_lds_dwordx4 v136, s[100:101]
	s_mov_b32 m0, s58
	s_nop 0
	global_load_lds_dwordx4 v134, s[100:101]
	s_waitcnt vmcnt(8)
	s_waitcnt lgkmcnt(0)
	s_barrier
	s_setprio 1
	s_waitcnt lgkmcnt(0)
	v_mfma_f32_16x16x32_bf16 v[62:65], v[142:145], v[184:187], v[62:65]
	v_mfma_f32_16x16x32_bf16 v[58:61], v[154:157], v[184:187], v[58:61]
	v_mfma_f32_16x16x32_bf16 v[46:49], v[142:145], v[192:195], v[46:49]
	v_mfma_f32_16x16x32_bf16 v[42:45], v[154:157], v[192:195], v[42:45]
	v_mfma_f32_16x16x32_bf16 v[30:33], v[142:145], v[208:211], v[30:33]
	v_mfma_f32_16x16x32_bf16 v[26:29], v[154:157], v[208:211], v[26:29]
	v_mfma_f32_16x16x32_bf16 v[14:17], v[142:145], v[226:229], v[14:17]
	v_mfma_f32_16x16x32_bf16 v[10:13], v[154:157], v[226:229], v[10:13]
	v_mfma_f32_16x16x32_bf16 v[62:65], v[146:149], v[188:191], v[62:65]
	v_mfma_f32_16x16x32_bf16 v[58:61], v[158:161], v[188:191], v[58:61]
	v_mfma_f32_16x16x32_bf16 v[46:49], v[146:149], v[196:199], v[46:49]
	v_mfma_f32_16x16x32_bf16 v[42:45], v[158:161], v[196:199], v[42:45]
	v_mfma_f32_16x16x32_bf16 v[30:33], v[146:149], v[222:225], v[30:33]
	v_mfma_f32_16x16x32_bf16 v[26:29], v[158:161], v[222:225], v[26:29]
	v_mfma_f32_16x16x32_bf16 v[14:17], v[146:149], v[230:233], v[14:17]
	v_mfma_f32_16x16x32_bf16 v[10:13], v[158:161], v[230:233], v[10:13]
	s_setprio 0
	s_setprio 1
	v_mfma_f32_16x16x32_bf16 v[54:57], v[162:165], v[184:187], v[54:57]
	v_mfma_f32_16x16x32_bf16 v[50:53], v[176:179], v[184:187], v[50:53]
	v_mfma_f32_16x16x32_bf16 v[38:41], v[162:165], v[192:195], v[38:41]
	v_mfma_f32_16x16x32_bf16 v[34:37], v[176:179], v[192:195], v[34:37]
	v_mfma_f32_16x16x32_bf16 v[22:25], v[162:165], v[208:211], v[22:25]
	v_mfma_f32_16x16x32_bf16 v[18:21], v[176:179], v[208:211], v[18:21]
	v_mfma_f32_16x16x32_bf16 v[6:9], v[162:165], v[226:229], v[6:9]
	v_mfma_f32_16x16x32_bf16 v[2:5], v[176:179], v[226:229], v[2:5]
	v_mfma_f32_16x16x32_bf16 v[54:57], v[166:169], v[188:191], v[54:57]
	v_mfma_f32_16x16x32_bf16 v[50:53], v[180:183], v[188:191], v[50:53]
	v_mfma_f32_16x16x32_bf16 v[38:41], v[166:169], v[196:199], v[38:41]
	v_mfma_f32_16x16x32_bf16 v[34:37], v[180:183], v[196:199], v[34:37]
	v_mfma_f32_16x16x32_bf16 v[22:25], v[166:169], v[222:225], v[22:25]
	v_mfma_f32_16x16x32_bf16 v[18:21], v[180:183], v[222:225], v[18:21]
	v_mfma_f32_16x16x32_bf16 v[6:9], v[166:169], v[230:233], v[6:9]
	v_mfma_f32_16x16x32_bf16 v[2:5], v[180:183], v[230:233], v[2:5]
	s_setprio 0
	s_barrier
	s_add_i32 s70, s70, 2
	s_add_u32 s68, s68, 0x100
	s_addc_u32 s69, s69, 0
	s_add_u32 s28, s28, 0x100
	s_addc_u32 s29, s29, 0
	s_cmp_gt_u32 s70, 29
	s_cbranch_scc0 .LBB0_351
	s_and_b64 vcc, exec, s[10:11]
	s_cbranch_vccz .LBB0_354
	s_barrier

.LBB0_662:
	s_ashr_i32 s11, s10, 31
	s_lshl_b64 s[12:13], s[10:11], 20
	s_add_u32 s12, s20, s12
	s_addc_u32 s13, s30, s13
	s_and_b64 s[14:15], s[0:1], exec
	s_cselect_b32 s11, s13, s25
	s_cselect_b32 s49, s12, s24
	s_ashr_i32 s9, s8, 31
	s_lshl_b64 s[14:15], s[8:9], 20
	s_add_u32 s14, s31, s14
	s_addc_u32 s15, s36, s15
	s_and_b64 s[28:29], s[0:1], exec
	s_cselect_b32 s9, s15, s17
	s_cselect_b32 s54, s14, s16
	s_add_u32 s55, s16, 0x100
	s_addc_u32 s56, s17, 0
	s_add_u32 s16, s24, 0x80080
	v_mov_b32_e32 v2, 0
	s_addc_u32 s17, s25, 0
	s_mov_b32 s57, -2
	v_mov_b32_e32 v3, v2
	v_mov_b32_e32 v4, v2
	v_mov_b32_e32 v5, v2
	v_mov_b32_e32 v6, v2
	v_mov_b32_e32 v7, v2
	v_mov_b32_e32 v8, v2
	v_mov_b32_e32 v9, v2
	v_mov_b32_e32 v10, v2
	v_mov_b32_e32 v11, v2
	v_mov_b32_e32 v12, v2
	v_mov_b32_e32 v13, v2
	v_mov_b32_e32 v18, v2
	v_mov_b32_e32 v19, v2
	v_mov_b32_e32 v20, v2
	v_mov_b32_e32 v21, v2
	v_mov_b32_e32 v26, v2
	v_mov_b32_e32 v27, v2
	v_mov_b32_e32 v28, v2
	v_mov_b32_e32 v29, v2
	v_mov_b32_e32 v34, v2
	v_mov_b32_e32 v35, v2
	v_mov_b32_e32 v36, v2
	v_mov_b32_e32 v37, v2
	v_mov_b32_e32 v42, v2
	v_mov_b32_e32 v43, v2
	v_mov_b32_e32 v44, v2
	v_mov_b32_e32 v45, v2
	v_mov_b32_e32 v50, v2
	v_mov_b32_e32 v51, v2
	v_mov_b32_e32 v52, v2
	v_mov_b32_e32 v53, v2
	v_mov_b32_e32 v14, v2
	v_mov_b32_e32 v15, v2
	v_mov_b32_e32 v16, v2
	v_mov_b32_e32 v17, v2
	v_mov_b32_e32 v22, v2
	v_mov_b32_e32 v23, v2
	v_mov_b32_e32 v24, v2
	v_mov_b32_e32 v25, v2
	v_mov_b32_e32 v30, v2
	v_mov_b32_e32 v31, v2
	v_mov_b32_e32 v32, v2
	v_mov_b32_e32 v33, v2
	v_mov_b32_e32 v38, v2
	v_mov_b32_e32 v39, v2
	v_mov_b32_e32 v40, v2
	v_mov_b32_e32 v41, v2
	v_mov_b32_e32 v46, v2
	v_mov_b32_e32 v47, v2
	v_mov_b32_e32 v48, v2
	v_mov_b32_e32 v49, v2
	v_mov_b32_e32 v54, v2
	v_mov_b32_e32 v55, v2
	v_mov_b32_e32 v56, v2
	v_mov_b32_e32 v57, v2
	v_mov_b32_e32 v58, v2
	v_mov_b32_e32 v59, v2
	v_mov_b32_e32 v60, v2
	v_mov_b32_e32 v61, v2
	v_mov_b32_e32 v62, v2
	v_mov_b32_e32 v63, v2
	v_mov_b32_e32 v64, v2
	v_mov_b32_e32 v65, v2
	v_mov_b32_e32 v66, v2
	v_mov_b32_e32 v67, v2
	v_mov_b32_e32 v68, v2
	v_mov_b32_e32 v69, v2
	v_mov_b32_e32 v70, v2
	v_mov_b32_e32 v71, v2
	v_mov_b32_e32 v72, v2
	v_mov_b32_e32 v73, v2
	v_mov_b32_e32 v74, v2
	v_mov_b32_e32 v75, v2
	v_mov_b32_e32 v76, v2
	v_mov_b32_e32 v77, v2
	v_mov_b32_e32 v82, v2
	v_mov_b32_e32 v83, v2
	v_mov_b32_e32 v84, v2
	v_mov_b32_e32 v85, v2
	v_mov_b32_e32 v90, v2
	v_mov_b32_e32 v91, v2
	v_mov_b32_e32 v92, v2
	v_mov_b32_e32 v93, v2
	v_mov_b32_e32 v98, v2
	v_mov_b32_e32 v99, v2
	v_mov_b32_e32 v100, v2
	v_mov_b32_e32 v101, v2
	v_mov_b32_e32 v106, v2
	v_mov_b32_e32 v107, v2
	v_mov_b32_e32 v108, v2
	v_mov_b32_e32 v109, v2
	v_mov_b32_e32 v114, v2
	v_mov_b32_e32 v115, v2
	v_mov_b32_e32 v116, v2
	v_mov_b32_e32 v117, v2
	v_mov_b32_e32 v78, v2
	v_mov_b32_e32 v79, v2
	v_mov_b32_e32 v80, v2
	v_mov_b32_e32 v81, v2
	v_mov_b32_e32 v86, v2
	v_mov_b32_e32 v87, v2
	v_mov_b32_e32 v88, v2
	v_mov_b32_e32 v89, v2
	v_mov_b32_e32 v94, v2
	v_mov_b32_e32 v95, v2
	v_mov_b32_e32 v96, v2
	v_mov_b32_e32 v97, v2
	v_mov_b32_e32 v102, v2
	v_mov_b32_e32 v103, v2
	v_mov_b32_e32 v104, v2
	v_mov_b32_e32 v105, v2
	v_mov_b32_e32 v110, v2
	v_mov_b32_e32 v111, v2
	v_mov_b32_e32 v112, v2
	v_mov_b32_e32 v113, v2
	v_mov_b32_e32 v118, v2
	v_mov_b32_e32 v119, v2
	v_mov_b32_e32 v120, v2
	v_mov_b32_e32 v121, v2
	v_mov_b32_e32 v122, v2
	v_mov_b32_e32 v123, v2
	v_mov_b32_e32 v124, v2
	v_mov_b32_e32 v125, v2
	v_mov_b32_e32 v126, v2
	v_mov_b32_e32 v127, v2
	v_mov_b32_e32 v128, v2
	v_mov_b32_e32 v129, v2
	v_add_u32_e32 v212, 0x10000, v147
.LBB0_663:
	s_add_u32 s24, s16, 0xfff80080
	s_addc_u32 s25, s17, -1
	s_add_i32 s58, 0, 0x10000
	s_cmp_eq_u32 s57, 28
	s_cselect_b32 s29, s11, s25
	s_cselect_b32 s28, s49, s24
	s_cselect_b32 s25, s9, s56
	s_cselect_b32 s24, s54, s55
	s_add_i32 s60, 0, 0x14000
	ds_read_b128 v[142:145], v212
	ds_read_b128 v[150:153], v212 offset:1024
	ds_read_b128 v[154:157], v212 offset:2048
	ds_read_b128 v[158:161], v212 offset:3072
	ds_read_b128 v[162:165], v212 offset:16384
	ds_read_b128 v[166:169], v212 offset:17408
	ds_read_b128 v[176:179], v212 offset:18432
	ds_read_b128 v[180:183], v212 offset:19456
	s_add_i32 m0, s38, 0xc000
	ds_read_b128 v[184:187], v149
	ds_read_b128 v[188:191], v149 offset:1024
	ds_read_b128 v[192:195], v149 offset:2048
	ds_read_b128 v[196:199], v149 offset:3072
	ds_read_b128 v[208:211], v149 offset:4096
	ds_read_b128 v[222:225], v149 offset:5120
	ds_read_b128 v[226:229], v149 offset:6144
	ds_read_b128 v[230:233], v149 offset:7168
	global_load_lds_dwordx4 v140, s[16:17]
	s_add_i32 m0, s38, 0xe000
	s_nop 0
	global_load_lds_dwordx4 v138, s[16:17]
	s_waitcnt vmcnt(8)
	s_waitcnt lgkmcnt(0)
	s_barrier
	s_setprio 1
	s_waitcnt lgkmcnt(0)
	v_mfma_f32_16x16x32_bf16 v[126:129], v[142:145], v[184:187], v[126:129]
	v_mfma_f32_16x16x32_bf16 v[122:125], v[154:157], v[184:187], v[122:125]
	v_mfma_f32_16x16x32_bf16 v[118:121], v[142:145], v[192:195], v[118:121]
	v_mfma_f32_16x16x32_bf16 v[110:113], v[154:157], v[192:195], v[110:113]
	v_mfma_f32_16x16x32_bf16 v[102:105], v[142:145], v[208:211], v[102:105]
	v_mfma_f32_16x16x32_bf16 v[94:97], v[154:157], v[208:211], v[94:97]
	v_mfma_f32_16x16x32_bf16 v[86:89], v[142:145], v[226:229], v[86:89]
	v_mfma_f32_16x16x32_bf16 v[78:81], v[154:157], v[226:229], v[78:81]
	v_mfma_f32_16x16x32_bf16 v[126:129], v[150:153], v[188:191], v[126:129]
	v_mfma_f32_16x16x32_bf16 v[122:125], v[158:161], v[188:191], v[122:125]
	v_mfma_f32_16x16x32_bf16 v[118:121], v[150:153], v[196:199], v[118:121]
	v_mfma_f32_16x16x32_bf16 v[110:113], v[158:161], v[196:199], v[110:113]
	v_mfma_f32_16x16x32_bf16 v[102:105], v[150:153], v[222:225], v[102:105]
	v_mfma_f32_16x16x32_bf16 v[94:97], v[158:161], v[222:225], v[94:97]
	v_mfma_f32_16x16x32_bf16 v[86:89], v[150:153], v[230:233], v[86:89]
	v_mfma_f32_16x16x32_bf16 v[78:81], v[158:161], v[230:233], v[78:81]
	s_setprio 0
	s_setprio 1
	v_mfma_f32_16x16x32_bf16 v[114:117], v[162:165], v[184:187], v[114:117]
	v_mfma_f32_16x16x32_bf16 v[106:109], v[176:179], v[184:187], v[106:109]
	v_mfma_f32_16x16x32_bf16 v[98:101], v[162:165], v[192:195], v[98:101]
	v_mfma_f32_16x16x32_bf16 v[90:93], v[176:179], v[192:195], v[90:93]
	v_mfma_f32_16x16x32_bf16 v[82:85], v[162:165], v[208:211], v[82:85]
	v_mfma_f32_16x16x32_bf16 v[74:77], v[176:179], v[208:211], v[74:77]
	v_mfma_f32_16x16x32_bf16 v[70:73], v[162:165], v[226:229], v[70:73]
	v_mfma_f32_16x16x32_bf16 v[66:69], v[176:179], v[226:229], v[66:69]
	v_mfma_f32_16x16x32_bf16 v[114:117], v[166:169], v[188:191], v[114:117]
	v_mfma_f32_16x16x32_bf16 v[106:109], v[180:183], v[188:191], v[106:109]
	v_mfma_f32_16x16x32_bf16 v[98:101], v[166:169], v[196:199], v[98:101]
	v_mfma_f32_16x16x32_bf16 v[90:93], v[180:183], v[196:199], v[90:93]
	v_mfma_f32_16x16x32_bf16 v[82:85], v[166:169], v[222:225], v[82:85]
	v_mfma_f32_16x16x32_bf16 v[74:77], v[180:183], v[222:225], v[74:77]
	v_mfma_f32_16x16x32_bf16 v[70:73], v[166:169], v[230:233], v[70:73]
	v_mfma_f32_16x16x32_bf16 v[66:69], v[180:183], v[230:233], v[66:69]
	s_setprio 0
	s_barrier
	s_add_i32 s58, s58, s37
	s_add_u32 s98, s24, s34
	s_addc_u32 s99, s25, s35
	s_mov_b32 m0, s58
	ds_read_b128 v[184:187], v149 offset:16384
	ds_read_b128 v[188:191], v149 offset:17408
	ds_read_b128 v[192:195], v149 offset:18432
	ds_read_b128 v[196:199], v149 offset:19456
	ds_read_b128 v[208:211], v149 offset:20480
	ds_read_b128 v[222:225], v149 offset:21504
	ds_read_b128 v[226:229], v149 offset:22528
	ds_read_b128 v[230:233], v149 offset:23552
	global_load_lds_dwordx4 v130, s[24:25]
	s_add_i32 m0, s58, 0x2000
	s_add_u32 s58, s24, 0x80000
	s_addc_u32 s59, s25, 0
	s_add_i32 s60, s60, s37
	global_load_lds_dwordx4 v132, s[24:25]
	s_mov_b32 m0, s60
	s_nop 0
	global_load_lds_dwordx4 v130, s[58:59]
	s_add_i32 m0, s60, 0x2000
	s_nop 0
	global_load_lds_dwordx4 v132, s[58:59]
	s_add_u32 s100, s28, s34
	s_addc_u32 s101, s29, s35
	s_mov_b32 m0, s38
	s_nop 0
	global_load_lds_dwordx4 v136, s[28:29]
	s_mov_b32 m0, s39
	s_nop 0
	global_load_lds_dwordx4 v134, s[28:29]
	s_waitcnt vmcnt(8)
	s_waitcnt lgkmcnt(0)
	s_barrier
	s_setprio 1
	s_waitcnt lgkmcnt(0)
	v_mfma_f32_16x16x32_bf16 v[62:65], v[142:145], v[184:187], v[62:65]
	v_mfma_f32_16x16x32_bf16 v[58:61], v[154:157], v[184:187], v[58:61]
	v_mfma_f32_16x16x32_bf16 v[54:57], v[142:145], v[192:195], v[54:57]
	v_mfma_f32_16x16x32_bf16 v[46:49], v[154:157], v[192:195], v[46:49]
	v_mfma_f32_16x16x32_bf16 v[38:41], v[142:145], v[208:211], v[38:41]
	v_mfma_f32_16x16x32_bf16 v[30:33], v[154:157], v[208:211], v[30:33]
	v_mfma_f32_16x16x32_bf16 v[22:25], v[142:145], v[226:229], v[22:25]
	v_mfma_f32_16x16x32_bf16 v[14:17], v[154:157], v[226:229], v[14:17]
	v_mfma_f32_16x16x32_bf16 v[62:65], v[150:153], v[188:191], v[62:65]
	v_mfma_f32_16x16x32_bf16 v[58:61], v[158:161], v[188:191], v[58:61]
	v_mfma_f32_16x16x32_bf16 v[54:57], v[150:153], v[196:199], v[54:57]
	v_mfma_f32_16x16x32_bf16 v[46:49], v[158:161], v[196:199], v[46:49]
	v_mfma_f32_16x16x32_bf16 v[38:41], v[150:153], v[222:225], v[38:41]
	v_mfma_f32_16x16x32_bf16 v[30:33], v[158:161], v[222:225], v[30:33]
	v_mfma_f32_16x16x32_bf16 v[22:25], v[150:153], v[230:233], v[22:25]
	v_mfma_f32_16x16x32_bf16 v[14:17], v[158:161], v[230:233], v[14:17]
	s_setprio 0
	s_setprio 1
	v_mfma_f32_16x16x32_bf16 v[50:53], v[162:165], v[184:187], v[50:53]
	v_mfma_f32_16x16x32_bf16 v[42:45], v[176:179], v[184:187], v[42:45]
	v_mfma_f32_16x16x32_bf16 v[34:37], v[162:165], v[192:195], v[34:37]
	v_mfma_f32_16x16x32_bf16 v[26:29], v[176:179], v[192:195], v[26:29]
	v_mfma_f32_16x16x32_bf16 v[18:21], v[162:165], v[208:211], v[18:21]
	v_mfma_f32_16x16x32_bf16 v[10:13], v[176:179], v[208:211], v[10:13]
	v_mfma_f32_16x16x32_bf16 v[6:9], v[162:165], v[226:229], v[6:9]
	v_mfma_f32_16x16x32_bf16 v[2:5], v[176:179], v[226:229], v[2:5]
	v_mfma_f32_16x16x32_bf16 v[50:53], v[166:169], v[188:191], v[50:53]
	v_mfma_f32_16x16x32_bf16 v[42:45], v[180:183], v[188:191], v[42:45]
	v_mfma_f32_16x16x32_bf16 v[34:37], v[166:169], v[196:199], v[34:37]
	v_mfma_f32_16x16x32_bf16 v[26:29], v[180:183], v[196:199], v[26:29]
	v_mfma_f32_16x16x32_bf16 v[18:21], v[166:169], v[222:225], v[18:21]
	v_mfma_f32_16x16x32_bf16 v[10:13], v[180:183], v[222:225], v[10:13]
	v_mfma_f32_16x16x32_bf16 v[6:9], v[166:169], v[230:233], v[6:9]
	v_mfma_f32_16x16x32_bf16 v[2:5], v[180:183], v[230:233], v[2:5]
	s_setprio 0
	s_barrier
	s_add_i32 s58, 0, 0x18000
	s_add_i32 s59, 0, 0x1c000
	ds_read_b128 v[142:145], v212 offset:32768
	ds_read_b128 v[150:153], v212 offset:33792
	ds_read_b128 v[154:157], v212 offset:34816
	ds_read_b128 v[158:161], v212 offset:35840
	ds_read_b128 v[162:165], v212 offset:49152
	ds_read_b128 v[166:169], v212 offset:50176
	ds_read_b128 v[176:179], v212 offset:51200
	ds_read_b128 v[180:183], v212 offset:52224
	s_add_u32 s28, s28, 0x80000
	s_addc_u32 s29, s29, 0
	s_mov_b32 m0, s40
	ds_read_b128 v[184:187], v149 offset:32768
	ds_read_b128 v[188:191], v149 offset:33792
	ds_read_b128 v[192:195], v149 offset:34816
	ds_read_b128 v[196:199], v149 offset:35840
	ds_read_b128 v[208:211], v149 offset:36864
	ds_read_b128 v[222:225], v149 offset:37888
	ds_read_b128 v[226:229], v149 offset:38912
	ds_read_b128 v[230:233], v149 offset:39936
	global_load_lds_dwordx4 v136, s[28:29]
	s_mov_b32 m0, s41
	s_nop 0
	global_load_lds_dwordx4 v134, s[28:29]
	s_waitcnt vmcnt(8)
	s_waitcnt lgkmcnt(0)
	s_barrier
	s_setprio 1
	s_waitcnt lgkmcnt(0)
	v_mfma_f32_16x16x32_bf16 v[126:129], v[142:145], v[184:187], v[126:129]
	v_mfma_f32_16x16x32_bf16 v[122:125], v[154:157], v[184:187], v[122:125]
	v_mfma_f32_16x16x32_bf16 v[118:121], v[142:145], v[192:195], v[118:121]
	v_mfma_f32_16x16x32_bf16 v[110:113], v[154:157], v[192:195], v[110:113]
	v_mfma_f32_16x16x32_bf16 v[102:105], v[142:145], v[208:211], v[102:105]
	v_mfma_f32_16x16x32_bf16 v[94:97], v[154:157], v[208:211], v[94:97]
	v_mfma_f32_16x16x32_bf16 v[86:89], v[142:145], v[226:229], v[86:89]
	v_mfma_f32_16x16x32_bf16 v[78:81], v[154:157], v[226:229], v[78:81]
	v_mfma_f32_16x16x32_bf16 v[126:129], v[150:153], v[188:191], v[126:129]
	v_mfma_f32_16x16x32_bf16 v[122:125], v[158:161], v[188:191], v[122:125]
	v_mfma_f32_16x16x32_bf16 v[118:121], v[150:153], v[196:199], v[118:121]
	v_mfma_f32_16x16x32_bf16 v[110:113], v[158:161], v[196:199], v[110:113]
	v_mfma_f32_16x16x32_bf16 v[102:105], v[150:153], v[222:225], v[102:105]
	v_mfma_f32_16x16x32_bf16 v[94:97], v[158:161], v[222:225], v[94:97]
	v_mfma_f32_16x16x32_bf16 v[86:89], v[150:153], v[230:233], v[86:89]
	v_mfma_f32_16x16x32_bf16 v[78:81], v[158:161], v[230:233], v[78:81]
	s_setprio 0
	s_setprio 1
	v_mfma_f32_16x16x32_bf16 v[114:117], v[162:165], v[184:187], v[114:117]
	v_mfma_f32_16x16x32_bf16 v[106:109], v[176:179], v[184:187], v[106:109]
	v_mfma_f32_16x16x32_bf16 v[98:101], v[162:165], v[192:195], v[98:101]
	v_mfma_f32_16x16x32_bf16 v[90:93], v[176:179], v[192:195], v[90:93]
	v_mfma_f32_16x16x32_bf16 v[82:85], v[162:165], v[208:211], v[82:85]
	v_mfma_f32_16x16x32_bf16 v[74:77], v[176:179], v[208:211], v[74:77]
	v_mfma_f32_16x16x32_bf16 v[70:73], v[162:165], v[226:229], v[70:73]
	v_mfma_f32_16x16x32_bf16 v[66:69], v[176:179], v[226:229], v[66:69]
	v_mfma_f32_16x16x32_bf16 v[114:117], v[166:169], v[188:191], v[114:117]
	v_mfma_f32_16x16x32_bf16 v[106:109], v[180:183], v[188:191], v[106:109]
	v_mfma_f32_16x16x32_bf16 v[98:101], v[166:169], v[196:199], v[98:101]
	v_mfma_f32_16x16x32_bf16 v[90:93], v[180:183], v[196:199], v[90:93]
	v_mfma_f32_16x16x32_bf16 v[82:85], v[166:169], v[222:225], v[82:85]
	v_mfma_f32_16x16x32_bf16 v[74:77], v[180:183], v[222:225], v[74:77]
	v_mfma_f32_16x16x32_bf16 v[70:73], v[166:169], v[230:233], v[70:73]
	v_mfma_f32_16x16x32_bf16 v[66:69], v[180:183], v[230:233], v[66:69]
	s_setprio 0
	s_barrier
	s_add_i32 s28, s58, s37
	s_mov_b32 m0, s28
	ds_read_b128 v[184:187], v149 offset:49152
	ds_read_b128 v[188:191], v149 offset:50176
	ds_read_b128 v[192:195], v149 offset:51200
	ds_read_b128 v[196:199], v149 offset:52224
	ds_read_b128 v[208:211], v149 offset:53248
	ds_read_b128 v[222:225], v149 offset:54272
	ds_read_b128 v[226:229], v149 offset:55296
	ds_read_b128 v[230:233], v149 offset:56320
	global_load_lds_dwordx4 v130, s[98:99]
	s_add_i32 m0, s28, 0x2000
	s_add_u32 s24, s24, 0x80080
	s_addc_u32 s25, s25, 0
	s_add_i32 s28, s59, s37
	global_load_lds_dwordx4 v132, s[98:99]
	s_mov_b32 m0, s28
	s_nop 0
	global_load_lds_dwordx4 v130, s[24:25]
	s_add_i32 m0, s28, 0x2000
	s_nop 0
	global_load_lds_dwordx4 v132, s[24:25]
	s_mov_b32 m0, s44
	s_nop 0
	global_load_lds_dwordx4 v136, s[100:101]
	s_mov_b32 m0, s45
	s_nop 0
	global_load_lds_dwordx4 v134, s[100:101]
	s_waitcnt vmcnt(8)
	s_waitcnt lgkmcnt(0)
	s_barrier
	s_setprio 1
	s_waitcnt lgkmcnt(0)
	v_mfma_f32_16x16x32_bf16 v[62:65], v[142:145], v[184:187], v[62:65]
	v_mfma_f32_16x16x32_bf16 v[58:61], v[154:157], v[184:187], v[58:61]
	v_mfma_f32_16x16x32_bf16 v[54:57], v[142:145], v[192:195], v[54:57]
	v_mfma_f32_16x16x32_bf16 v[46:49], v[154:157], v[192:195], v[46:49]
	v_mfma_f32_16x16x32_bf16 v[38:41], v[142:145], v[208:211], v[38:41]
	v_mfma_f32_16x16x32_bf16 v[30:33], v[154:157], v[208:211], v[30:33]
	v_mfma_f32_16x16x32_bf16 v[22:25], v[142:145], v[226:229], v[22:25]
	v_mfma_f32_16x16x32_bf16 v[14:17], v[154:157], v[226:229], v[14:17]
	v_mfma_f32_16x16x32_bf16 v[62:65], v[150:153], v[188:191], v[62:65]
	v_mfma_f32_16x16x32_bf16 v[58:61], v[158:161], v[188:191], v[58:61]
	v_mfma_f32_16x16x32_bf16 v[54:57], v[150:153], v[196:199], v[54:57]
	v_mfma_f32_16x16x32_bf16 v[46:49], v[158:161], v[196:199], v[46:49]
	v_mfma_f32_16x16x32_bf16 v[38:41], v[150:153], v[222:225], v[38:41]
	v_mfma_f32_16x16x32_bf16 v[30:33], v[158:161], v[222:225], v[30:33]
	v_mfma_f32_16x16x32_bf16 v[22:25], v[150:153], v[230:233], v[22:25]
	v_mfma_f32_16x16x32_bf16 v[14:17], v[158:161], v[230:233], v[14:17]
	s_setprio 0
	s_setprio 1
	v_mfma_f32_16x16x32_bf16 v[50:53], v[162:165], v[184:187], v[50:53]
	v_mfma_f32_16x16x32_bf16 v[42:45], v[176:179], v[184:187], v[42:45]
	v_mfma_f32_16x16x32_bf16 v[34:37], v[162:165], v[192:195], v[34:37]
	v_mfma_f32_16x16x32_bf16 v[26:29], v[176:179], v[192:195], v[26:29]
	v_mfma_f32_16x16x32_bf16 v[18:21], v[162:165], v[208:211], v[18:21]
	v_mfma_f32_16x16x32_bf16 v[10:13], v[176:179], v[208:211], v[10:13]
	v_mfma_f32_16x16x32_bf16 v[6:9], v[162:165], v[226:229], v[6:9]
	v_mfma_f32_16x16x32_bf16 v[2:5], v[176:179], v[226:229], v[2:5]
	v_mfma_f32_16x16x32_bf16 v[50:53], v[166:169], v[188:191], v[50:53]
	v_mfma_f32_16x16x32_bf16 v[42:45], v[180:183], v[188:191], v[42:45]
	v_mfma_f32_16x16x32_bf16 v[34:37], v[166:169], v[196:199], v[34:37]
	v_mfma_f32_16x16x32_bf16 v[26:29], v[180:183], v[196:199], v[26:29]
	v_mfma_f32_16x16x32_bf16 v[18:21], v[166:169], v[222:225], v[18:21]
	v_mfma_f32_16x16x32_bf16 v[10:13], v[180:183], v[222:225], v[10:13]
	v_mfma_f32_16x16x32_bf16 v[6:9], v[166:169], v[230:233], v[6:9]
	v_mfma_f32_16x16x32_bf16 v[2:5], v[180:183], v[230:233], v[2:5]
	s_setprio 0
	s_barrier
	s_add_i32 s57, s57, 2
	s_add_u32 s55, s55, 0x100
	s_addc_u32 s56, s56, 0
	s_add_u32 s16, s16, 0x100
	s_addc_u32 s17, s17, 0
	s_cmp_gt_u32 s57, 29
	s_cbranch_scc0 .LBB0_663
	s_and_b64 vcc, exec, s[6:7]
	s_cbranch_vccz .LBB0_666
	s_barrier

.LBB0_1028:
	s_ashr_i32 s13, s12, 31
	s_lshl_b64 s[14:15], s[12:13], 20
	s_add_u32 s14, s42, s14
	s_addc_u32 s15, s43, s15
	s_and_b64 s[16:17], s[36:37], exec
	s_cselect_b32 s13, s15, s29
	s_cselect_b32 s59, s14, s28
	s_ashr_i32 s11, s10, 31
	s_lshl_b64 s[16:17], s[10:11], 20
	s_add_u32 s16, s38, s16
	s_addc_u32 s17, s39, s17
	s_and_b64 s[30:31], s[36:37], exec
	s_cselect_b32 s11, s17, s25
	s_cselect_b32 s60, s16, s24
	s_add_u32 s61, s24, 0x100
	s_addc_u32 s62, s25, 0
	s_add_u32 s24, s28, 0x80080
	v_mov_b32_e32 v2, 0
	s_addc_u32 s25, s29, 0
	s_mov_b32 s63, -2
	v_mov_b32_e32 v3, v2
	v_mov_b32_e32 v4, v2
	v_mov_b32_e32 v5, v2
	v_mov_b32_e32 v6, v2
	v_mov_b32_e32 v7, v2
	v_mov_b32_e32 v8, v2
	v_mov_b32_e32 v9, v2
	v_mov_b32_e32 v18, v2
	v_mov_b32_e32 v19, v2
	v_mov_b32_e32 v20, v2
	v_mov_b32_e32 v21, v2
	v_mov_b32_e32 v22, v2
	v_mov_b32_e32 v23, v2
	v_mov_b32_e32 v24, v2
	v_mov_b32_e32 v25, v2
	v_mov_b32_e32 v34, v2
	v_mov_b32_e32 v35, v2
	v_mov_b32_e32 v36, v2
	v_mov_b32_e32 v37, v2
	v_mov_b32_e32 v38, v2
	v_mov_b32_e32 v39, v2
	v_mov_b32_e32 v40, v2
	v_mov_b32_e32 v41, v2
	v_mov_b32_e32 v50, v2
	v_mov_b32_e32 v51, v2
	v_mov_b32_e32 v52, v2
	v_mov_b32_e32 v53, v2
	v_mov_b32_e32 v54, v2
	v_mov_b32_e32 v55, v2
	v_mov_b32_e32 v56, v2
	v_mov_b32_e32 v57, v2
	v_mov_b32_e32 v10, v2
	v_mov_b32_e32 v11, v2
	v_mov_b32_e32 v12, v2
	v_mov_b32_e32 v13, v2
	v_mov_b32_e32 v14, v2
	v_mov_b32_e32 v15, v2
	v_mov_b32_e32 v16, v2
	v_mov_b32_e32 v17, v2
	v_mov_b32_e32 v26, v2
	v_mov_b32_e32 v27, v2
	v_mov_b32_e32 v28, v2
	v_mov_b32_e32 v29, v2
	v_mov_b32_e32 v30, v2
	v_mov_b32_e32 v31, v2
	v_mov_b32_e32 v32, v2
	v_mov_b32_e32 v33, v2
	v_mov_b32_e32 v42, v2
	v_mov_b32_e32 v43, v2
	v_mov_b32_e32 v44, v2
	v_mov_b32_e32 v45, v2
	v_mov_b32_e32 v46, v2
	v_mov_b32_e32 v47, v2
	v_mov_b32_e32 v48, v2
	v_mov_b32_e32 v49, v2
	v_mov_b32_e32 v58, v2
	v_mov_b32_e32 v59, v2
	v_mov_b32_e32 v60, v2
	v_mov_b32_e32 v61, v2
	v_mov_b32_e32 v62, v2
	v_mov_b32_e32 v63, v2
	v_mov_b32_e32 v64, v2
	v_mov_b32_e32 v65, v2
	v_mov_b32_e32 v66, v2
	v_mov_b32_e32 v67, v2
	v_mov_b32_e32 v68, v2
	v_mov_b32_e32 v69, v2
	v_mov_b32_e32 v70, v2
	v_mov_b32_e32 v71, v2
	v_mov_b32_e32 v72, v2
	v_mov_b32_e32 v73, v2
	v_mov_b32_e32 v82, v2
	v_mov_b32_e32 v83, v2
	v_mov_b32_e32 v84, v2
	v_mov_b32_e32 v85, v2
	v_mov_b32_e32 v86, v2
	v_mov_b32_e32 v87, v2
	v_mov_b32_e32 v88, v2
	v_mov_b32_e32 v89, v2
	v_mov_b32_e32 v98, v2
	v_mov_b32_e32 v99, v2
	v_mov_b32_e32 v100, v2
	v_mov_b32_e32 v101, v2
	v_mov_b32_e32 v102, v2
	v_mov_b32_e32 v103, v2
	v_mov_b32_e32 v104, v2
	v_mov_b32_e32 v105, v2
	v_mov_b32_e32 v122, v2
	v_mov_b32_e32 v123, v2
	v_mov_b32_e32 v124, v2
	v_mov_b32_e32 v125, v2
	v_mov_b32_e32 v126, v2
	v_mov_b32_e32 v127, v2
	v_mov_b32_e32 v128, v2
	v_mov_b32_e32 v129, v2
	v_mov_b32_e32 v74, v2
	v_mov_b32_e32 v75, v2
	v_mov_b32_e32 v76, v2
	v_mov_b32_e32 v77, v2
	v_mov_b32_e32 v78, v2
	v_mov_b32_e32 v79, v2
	v_mov_b32_e32 v80, v2
	v_mov_b32_e32 v81, v2
	v_mov_b32_e32 v90, v2
	v_mov_b32_e32 v91, v2
	v_mov_b32_e32 v92, v2
	v_mov_b32_e32 v93, v2
	v_mov_b32_e32 v94, v2
	v_mov_b32_e32 v95, v2
	v_mov_b32_e32 v96, v2
	v_mov_b32_e32 v97, v2
	v_mov_b32_e32 v132, v2
	v_mov_b32_e32 v133, v2
	v_mov_b32_e32 v134, v2
	v_mov_b32_e32 v135, v2
	v_mov_b32_e32 v136, v2
	v_mov_b32_e32 v137, v2
	v_mov_b32_e32 v138, v2
	v_mov_b32_e32 v139, v2
	v_mov_b32_e32 v140, v2
	v_mov_b32_e32 v141, v2
	v_mov_b32_e32 v142, v2
	v_mov_b32_e32 v143, v2
	v_mov_b32_e32 v144, v2
	v_mov_b32_e32 v145, v2
	v_mov_b32_e32 v146, v2
	v_mov_b32_e32 v147, v2
	v_add_u32_e32 v212, 0x10000, v195
.LBB0_1029:
	s_add_u32 s28, s24, 0xfff80080
	s_addc_u32 s29, s25, -1
	s_add_i32 s68, 0, 0x10000
	s_cmp_eq_u32 s63, 28
	s_cselect_b32 s31, s13, s29
	s_cselect_b32 s30, s59, s28
	s_cselect_b32 s29, s11, s62
	s_cselect_b32 s28, s60, s61
	s_add_i32 s70, 0, 0x14000
	ds_read_b128 v[106:109], v212
	ds_read_b128 v[110:113], v212 offset:1024
	ds_read_b128 v[114:117], v212 offset:2048
	ds_read_b128 v[118:121], v212 offset:3072
	ds_read_b128 v[148:151], v212 offset:16384
	ds_read_b128 v[152:155], v212 offset:17408
	ds_read_b128 v[156:159], v212 offset:18432
	ds_read_b128 v[160:163], v212 offset:19456
	s_add_i32 m0, s45, 0xc000
	ds_read_b128 v[164:167], v197
	ds_read_b128 v[182:185], v197 offset:1024
	ds_read_b128 v[186:189], v197 offset:2048
	ds_read_b128 v[190:193], v197 offset:3072
	ds_read_b128 v[208:211], v197 offset:4096
	ds_read_b128 v[222:225], v197 offset:5120
	ds_read_b128 v[226:229], v197 offset:6144
	ds_read_b128 v[230:233], v197 offset:7168
	global_load_lds_dwordx4 v180, s[24:25]
	s_add_i32 m0, s45, 0xe000
	s_nop 0
	global_load_lds_dwordx4 v178, s[24:25]
	s_waitcnt vmcnt(8)
	s_waitcnt lgkmcnt(0)
	s_barrier
	s_setprio 1
	s_waitcnt lgkmcnt(0)
	v_mfma_f32_16x16x32_bf16 v[144:147], v[106:109], v[164:167], v[144:147]
	v_mfma_f32_16x16x32_bf16 v[140:143], v[114:117], v[164:167], v[140:143]
	v_mfma_f32_16x16x32_bf16 v[136:139], v[106:109], v[186:189], v[136:139]
	v_mfma_f32_16x16x32_bf16 v[132:135], v[114:117], v[186:189], v[132:135]
	v_mfma_f32_16x16x32_bf16 v[94:97], v[106:109], v[208:211], v[94:97]
	v_mfma_f32_16x16x32_bf16 v[90:93], v[114:117], v[208:211], v[90:93]
	v_mfma_f32_16x16x32_bf16 v[78:81], v[106:109], v[226:229], v[78:81]
	v_mfma_f32_16x16x32_bf16 v[74:77], v[114:117], v[226:229], v[74:77]
	v_mfma_f32_16x16x32_bf16 v[144:147], v[110:113], v[182:185], v[144:147]
	v_mfma_f32_16x16x32_bf16 v[140:143], v[118:121], v[182:185], v[140:143]
	v_mfma_f32_16x16x32_bf16 v[136:139], v[110:113], v[190:193], v[136:139]
	v_mfma_f32_16x16x32_bf16 v[132:135], v[118:121], v[190:193], v[132:135]
	v_mfma_f32_16x16x32_bf16 v[94:97], v[110:113], v[222:225], v[94:97]
	v_mfma_f32_16x16x32_bf16 v[90:93], v[118:121], v[222:225], v[90:93]
	v_mfma_f32_16x16x32_bf16 v[78:81], v[110:113], v[230:233], v[78:81]
	v_mfma_f32_16x16x32_bf16 v[74:77], v[118:121], v[230:233], v[74:77]
	s_setprio 0
	s_setprio 1
	v_mfma_f32_16x16x32_bf16 v[126:129], v[148:151], v[164:167], v[126:129]
	v_mfma_f32_16x16x32_bf16 v[122:125], v[156:159], v[164:167], v[122:125]
	v_mfma_f32_16x16x32_bf16 v[102:105], v[148:151], v[186:189], v[102:105]
	v_mfma_f32_16x16x32_bf16 v[98:101], v[156:159], v[186:189], v[98:101]
	v_mfma_f32_16x16x32_bf16 v[86:89], v[148:151], v[208:211], v[86:89]
	v_mfma_f32_16x16x32_bf16 v[82:85], v[156:159], v[208:211], v[82:85]
	v_mfma_f32_16x16x32_bf16 v[70:73], v[148:151], v[226:229], v[70:73]
	v_mfma_f32_16x16x32_bf16 v[66:69], v[156:159], v[226:229], v[66:69]
	v_mfma_f32_16x16x32_bf16 v[126:129], v[152:155], v[182:185], v[126:129]
	v_mfma_f32_16x16x32_bf16 v[122:125], v[160:163], v[182:185], v[122:125]
	v_mfma_f32_16x16x32_bf16 v[102:105], v[152:155], v[190:193], v[102:105]
	v_mfma_f32_16x16x32_bf16 v[98:101], v[160:163], v[190:193], v[98:101]
	v_mfma_f32_16x16x32_bf16 v[86:89], v[152:155], v[222:225], v[86:89]
	v_mfma_f32_16x16x32_bf16 v[82:85], v[160:163], v[222:225], v[82:85]
	v_mfma_f32_16x16x32_bf16 v[70:73], v[152:155], v[230:233], v[70:73]
	v_mfma_f32_16x16x32_bf16 v[66:69], v[160:163], v[230:233], v[66:69]
	s_setprio 0
	s_barrier
	s_add_i32 s68, s68, s44
	s_add_u32 s98, s28, s34
	s_addc_u32 s99, s29, s35
	s_mov_b32 m0, s68
	ds_read_b128 v[164:167], v197 offset:16384
	ds_read_b128 v[182:185], v197 offset:17408
	ds_read_b128 v[186:189], v197 offset:18432
	ds_read_b128 v[190:193], v197 offset:19456
	ds_read_b128 v[208:211], v197 offset:20480
	ds_read_b128 v[222:225], v197 offset:21504
	ds_read_b128 v[226:229], v197 offset:22528
	ds_read_b128 v[230:233], v197 offset:23552
	global_load_lds_dwordx4 v130, s[28:29]
	s_add_i32 m0, s68, 0x2000
	s_add_u32 s68, s28, 0x80000
	s_addc_u32 s69, s29, 0
	s_add_i32 s70, s70, s44
	global_load_lds_dwordx4 v168, s[28:29]
	s_mov_b32 m0, s70
	s_nop 0
	global_load_lds_dwordx4 v130, s[68:69]
	s_add_i32 m0, s70, 0x2000
	s_nop 0
	global_load_lds_dwordx4 v168, s[68:69]
	s_add_u32 s100, s30, s34
	s_addc_u32 s101, s31, s35
	s_mov_b32 m0, s45
	s_nop 0
	global_load_lds_dwordx4 v176, s[30:31]
	s_mov_b32 m0, s46
	s_nop 0
	global_load_lds_dwordx4 v170, s[30:31]
	s_waitcnt vmcnt(8)
	s_waitcnt lgkmcnt(0)
	s_barrier
	s_setprio 1
	s_waitcnt lgkmcnt(0)
	v_mfma_f32_16x16x32_bf16 v[62:65], v[106:109], v[164:167], v[62:65]
	v_mfma_f32_16x16x32_bf16 v[58:61], v[114:117], v[164:167], v[58:61]
	v_mfma_f32_16x16x32_bf16 v[46:49], v[106:109], v[186:189], v[46:49]
	v_mfma_f32_16x16x32_bf16 v[42:45], v[114:117], v[186:189], v[42:45]
	v_mfma_f32_16x16x32_bf16 v[30:33], v[106:109], v[208:211], v[30:33]
	v_mfma_f32_16x16x32_bf16 v[26:29], v[114:117], v[208:211], v[26:29]
	v_mfma_f32_16x16x32_bf16 v[14:17], v[106:109], v[226:229], v[14:17]
	v_mfma_f32_16x16x32_bf16 v[10:13], v[114:117], v[226:229], v[10:13]
	v_mfma_f32_16x16x32_bf16 v[62:65], v[110:113], v[182:185], v[62:65]
	v_mfma_f32_16x16x32_bf16 v[58:61], v[118:121], v[182:185], v[58:61]
	v_mfma_f32_16x16x32_bf16 v[46:49], v[110:113], v[190:193], v[46:49]
	v_mfma_f32_16x16x32_bf16 v[42:45], v[118:121], v[190:193], v[42:45]
	v_mfma_f32_16x16x32_bf16 v[30:33], v[110:113], v[222:225], v[30:33]
	v_mfma_f32_16x16x32_bf16 v[26:29], v[118:121], v[222:225], v[26:29]
	v_mfma_f32_16x16x32_bf16 v[14:17], v[110:113], v[230:233], v[14:17]
	v_mfma_f32_16x16x32_bf16 v[10:13], v[118:121], v[230:233], v[10:13]
	s_setprio 0
	s_setprio 1
	v_mfma_f32_16x16x32_bf16 v[54:57], v[148:151], v[164:167], v[54:57]
	v_mfma_f32_16x16x32_bf16 v[50:53], v[156:159], v[164:167], v[50:53]
	v_mfma_f32_16x16x32_bf16 v[38:41], v[148:151], v[186:189], v[38:41]
	v_mfma_f32_16x16x32_bf16 v[34:37], v[156:159], v[186:189], v[34:37]
	v_mfma_f32_16x16x32_bf16 v[22:25], v[148:151], v[208:211], v[22:25]
	v_mfma_f32_16x16x32_bf16 v[18:21], v[156:159], v[208:211], v[18:21]
	v_mfma_f32_16x16x32_bf16 v[6:9], v[148:151], v[226:229], v[6:9]
	v_mfma_f32_16x16x32_bf16 v[2:5], v[156:159], v[226:229], v[2:5]
	v_mfma_f32_16x16x32_bf16 v[54:57], v[152:155], v[182:185], v[54:57]
	v_mfma_f32_16x16x32_bf16 v[50:53], v[160:163], v[182:185], v[50:53]
	v_mfma_f32_16x16x32_bf16 v[38:41], v[152:155], v[190:193], v[38:41]
	v_mfma_f32_16x16x32_bf16 v[34:37], v[160:163], v[190:193], v[34:37]
	v_mfma_f32_16x16x32_bf16 v[22:25], v[152:155], v[222:225], v[22:25]
	v_mfma_f32_16x16x32_bf16 v[18:21], v[160:163], v[222:225], v[18:21]
	v_mfma_f32_16x16x32_bf16 v[6:9], v[152:155], v[230:233], v[6:9]
	v_mfma_f32_16x16x32_bf16 v[2:5], v[160:163], v[230:233], v[2:5]
	s_setprio 0
	s_barrier
	s_add_i32 s68, 0, 0x18000
	s_add_i32 s69, 0, 0x1c000
	ds_read_b128 v[106:109], v212 offset:32768
	ds_read_b128 v[110:113], v212 offset:33792
	ds_read_b128 v[114:117], v212 offset:34816
	ds_read_b128 v[118:121], v212 offset:35840
	ds_read_b128 v[148:151], v212 offset:49152
	ds_read_b128 v[152:155], v212 offset:50176
	ds_read_b128 v[156:159], v212 offset:51200
	ds_read_b128 v[160:163], v212 offset:52224
	s_add_u32 s30, s30, 0x80000
	s_addc_u32 s31, s31, 0
	s_mov_b32 m0, s47
	ds_read_b128 v[164:167], v197 offset:32768
	ds_read_b128 v[182:185], v197 offset:33792
	ds_read_b128 v[186:189], v197 offset:34816
	ds_read_b128 v[190:193], v197 offset:35840
	ds_read_b128 v[208:211], v197 offset:36864
	ds_read_b128 v[222:225], v197 offset:37888
	ds_read_b128 v[226:229], v197 offset:38912
	ds_read_b128 v[230:233], v197 offset:39936
	global_load_lds_dwordx4 v176, s[30:31]
	s_mov_b32 m0, s48
	s_nop 0
	global_load_lds_dwordx4 v170, s[30:31]
	s_waitcnt vmcnt(8)
	s_waitcnt lgkmcnt(0)
	s_barrier
	s_setprio 1
	s_waitcnt lgkmcnt(0)
	v_mfma_f32_16x16x32_bf16 v[144:147], v[106:109], v[164:167], v[144:147]
	v_mfma_f32_16x16x32_bf16 v[140:143], v[114:117], v[164:167], v[140:143]
	v_mfma_f32_16x16x32_bf16 v[136:139], v[106:109], v[186:189], v[136:139]
	v_mfma_f32_16x16x32_bf16 v[132:135], v[114:117], v[186:189], v[132:135]
	v_mfma_f32_16x16x32_bf16 v[94:97], v[106:109], v[208:211], v[94:97]
	v_mfma_f32_16x16x32_bf16 v[90:93], v[114:117], v[208:211], v[90:93]
	v_mfma_f32_16x16x32_bf16 v[78:81], v[106:109], v[226:229], v[78:81]
	v_mfma_f32_16x16x32_bf16 v[74:77], v[114:117], v[226:229], v[74:77]
	v_mfma_f32_16x16x32_bf16 v[144:147], v[110:113], v[182:185], v[144:147]
	v_mfma_f32_16x16x32_bf16 v[140:143], v[118:121], v[182:185], v[140:143]
	v_mfma_f32_16x16x32_bf16 v[136:139], v[110:113], v[190:193], v[136:139]
	v_mfma_f32_16x16x32_bf16 v[132:135], v[118:121], v[190:193], v[132:135]
	v_mfma_f32_16x16x32_bf16 v[94:97], v[110:113], v[222:225], v[94:97]
	v_mfma_f32_16x16x32_bf16 v[90:93], v[118:121], v[222:225], v[90:93]
	v_mfma_f32_16x16x32_bf16 v[78:81], v[110:113], v[230:233], v[78:81]
	v_mfma_f32_16x16x32_bf16 v[74:77], v[118:121], v[230:233], v[74:77]
	s_setprio 0
	s_setprio 1
	v_mfma_f32_16x16x32_bf16 v[126:129], v[148:151], v[164:167], v[126:129]
	v_mfma_f32_16x16x32_bf16 v[122:125], v[156:159], v[164:167], v[122:125]
	v_mfma_f32_16x16x32_bf16 v[102:105], v[148:151], v[186:189], v[102:105]
	v_mfma_f32_16x16x32_bf16 v[98:101], v[156:159], v[186:189], v[98:101]
	v_mfma_f32_16x16x32_bf16 v[86:89], v[148:151], v[208:211], v[86:89]
	v_mfma_f32_16x16x32_bf16 v[82:85], v[156:159], v[208:211], v[82:85]
	v_mfma_f32_16x16x32_bf16 v[70:73], v[148:151], v[226:229], v[70:73]
	v_mfma_f32_16x16x32_bf16 v[66:69], v[156:159], v[226:229], v[66:69]
	v_mfma_f32_16x16x32_bf16 v[126:129], v[152:155], v[182:185], v[126:129]
	v_mfma_f32_16x16x32_bf16 v[122:125], v[160:163], v[182:185], v[122:125]
	v_mfma_f32_16x16x32_bf16 v[102:105], v[152:155], v[190:193], v[102:105]
	v_mfma_f32_16x16x32_bf16 v[98:101], v[160:163], v[190:193], v[98:101]
	v_mfma_f32_16x16x32_bf16 v[86:89], v[152:155], v[222:225], v[86:89]
	v_mfma_f32_16x16x32_bf16 v[82:85], v[160:163], v[222:225], v[82:85]
	v_mfma_f32_16x16x32_bf16 v[70:73], v[152:155], v[230:233], v[70:73]
	v_mfma_f32_16x16x32_bf16 v[66:69], v[160:163], v[230:233], v[66:69]
	s_setprio 0
	s_barrier
	s_add_i32 s30, s68, s44
	s_mov_b32 m0, s30
	ds_read_b128 v[164:167], v197 offset:49152
	ds_read_b128 v[182:185], v197 offset:50176
	ds_read_b128 v[186:189], v197 offset:51200
	ds_read_b128 v[190:193], v197 offset:52224
	ds_read_b128 v[208:211], v197 offset:53248
	ds_read_b128 v[222:225], v197 offset:54272
	ds_read_b128 v[226:229], v197 offset:55296
	ds_read_b128 v[230:233], v197 offset:56320
	global_load_lds_dwordx4 v130, s[98:99]
	s_add_i32 m0, s30, 0x2000
	s_add_u32 s28, s28, 0x80080
	s_addc_u32 s29, s29, 0
	s_add_i32 s30, s69, s44
	global_load_lds_dwordx4 v168, s[98:99]
	s_mov_b32 m0, s30
	s_nop 0
	global_load_lds_dwordx4 v130, s[28:29]
	s_add_i32 m0, s30, 0x2000
	s_nop 0
	global_load_lds_dwordx4 v168, s[28:29]
	s_mov_b32 m0, s54
	s_nop 0
	global_load_lds_dwordx4 v176, s[100:101]
	s_mov_b32 m0, s55
	s_nop 0
	global_load_lds_dwordx4 v170, s[100:101]
	s_waitcnt vmcnt(8)
	s_waitcnt lgkmcnt(0)
	s_barrier
	s_setprio 1
	s_waitcnt lgkmcnt(0)
	v_mfma_f32_16x16x32_bf16 v[62:65], v[106:109], v[164:167], v[62:65]
	v_mfma_f32_16x16x32_bf16 v[58:61], v[114:117], v[164:167], v[58:61]
	v_mfma_f32_16x16x32_bf16 v[46:49], v[106:109], v[186:189], v[46:49]
	v_mfma_f32_16x16x32_bf16 v[42:45], v[114:117], v[186:189], v[42:45]
	v_mfma_f32_16x16x32_bf16 v[30:33], v[106:109], v[208:211], v[30:33]
	v_mfma_f32_16x16x32_bf16 v[26:29], v[114:117], v[208:211], v[26:29]
	v_mfma_f32_16x16x32_bf16 v[14:17], v[106:109], v[226:229], v[14:17]
	v_mfma_f32_16x16x32_bf16 v[10:13], v[114:117], v[226:229], v[10:13]
	v_mfma_f32_16x16x32_bf16 v[62:65], v[110:113], v[182:185], v[62:65]
	v_mfma_f32_16x16x32_bf16 v[58:61], v[118:121], v[182:185], v[58:61]
	v_mfma_f32_16x16x32_bf16 v[46:49], v[110:113], v[190:193], v[46:49]
	v_mfma_f32_16x16x32_bf16 v[42:45], v[118:121], v[190:193], v[42:45]
	v_mfma_f32_16x16x32_bf16 v[30:33], v[110:113], v[222:225], v[30:33]
	v_mfma_f32_16x16x32_bf16 v[26:29], v[118:121], v[222:225], v[26:29]
	v_mfma_f32_16x16x32_bf16 v[14:17], v[110:113], v[230:233], v[14:17]
	v_mfma_f32_16x16x32_bf16 v[10:13], v[118:121], v[230:233], v[10:13]
	s_setprio 0
	s_setprio 1
	v_mfma_f32_16x16x32_bf16 v[54:57], v[148:151], v[164:167], v[54:57]
	v_mfma_f32_16x16x32_bf16 v[50:53], v[156:159], v[164:167], v[50:53]
	v_mfma_f32_16x16x32_bf16 v[38:41], v[148:151], v[186:189], v[38:41]
	v_mfma_f32_16x16x32_bf16 v[34:37], v[156:159], v[186:189], v[34:37]
	v_mfma_f32_16x16x32_bf16 v[22:25], v[148:151], v[208:211], v[22:25]
	v_mfma_f32_16x16x32_bf16 v[18:21], v[156:159], v[208:211], v[18:21]
	v_mfma_f32_16x16x32_bf16 v[6:9], v[148:151], v[226:229], v[6:9]
	v_mfma_f32_16x16x32_bf16 v[2:5], v[156:159], v[226:229], v[2:5]
	v_mfma_f32_16x16x32_bf16 v[54:57], v[152:155], v[182:185], v[54:57]
	v_mfma_f32_16x16x32_bf16 v[50:53], v[160:163], v[182:185], v[50:53]
	v_mfma_f32_16x16x32_bf16 v[38:41], v[152:155], v[190:193], v[38:41]
	v_mfma_f32_16x16x32_bf16 v[34:37], v[160:163], v[190:193], v[34:37]
	v_mfma_f32_16x16x32_bf16 v[22:25], v[152:155], v[222:225], v[22:25]
	v_mfma_f32_16x16x32_bf16 v[18:21], v[160:163], v[222:225], v[18:21]
	v_mfma_f32_16x16x32_bf16 v[6:9], v[152:155], v[230:233], v[6:9]
	v_mfma_f32_16x16x32_bf16 v[2:5], v[160:163], v[230:233], v[2:5]
	s_setprio 0
	s_barrier
	s_add_i32 s63, s63, 2
	s_add_u32 s61, s61, 0x100
	s_addc_u32 s62, s62, 0
	s_add_u32 s24, s24, 0x100
	s_addc_u32 s25, s25, 0
	s_cmp_gt_u32 s63, 29
	s_cbranch_scc0 .LBB0_1029
	s_and_b64 vcc, exec, s[8:9]
	s_cbranch_vccz .LBB0_1032
	s_barrier

.LBB0_1048:
	s_ashr_i32 s11, s10, 31
	s_lshl_b64 s[12:13], s[10:11], 9
	s_add_u32 s12, s36, s12
	s_addc_u32 s13, s37, s13
	s_and_b64 s[14:15], s[0:1], exec
	s_cselect_b32 s11, s13, s25
	s_cselect_b32 s57, s12, s24
	s_ashr_i32 s9, s8, 31
	s_lshl_b64 s[14:15], s[8:9], 20
	s_add_u32 s14, s38, s14
	s_addc_u32 s15, s39, s15
	s_and_b64 s[28:29], s[0:1], exec
	s_cselect_b32 s9, s15, s17
	s_cselect_b32 s58, s14, s16
	s_add_u32 s59, s16, 0x100
	s_addc_u32 s60, s17, 0
	s_add_u32 s16, s24, 0x300100
	v_mov_b32_e32 v2, 0
	s_addc_u32 s17, s25, 0
	s_mov_b32 s61, -2
	v_mov_b32_e32 v3, v2
	v_mov_b32_e32 v4, v2
	v_mov_b32_e32 v5, v2
	v_mov_b32_e32 v6, v2
	v_mov_b32_e32 v7, v2
	v_mov_b32_e32 v8, v2
	v_mov_b32_e32 v9, v2
	v_mov_b32_e32 v18, v2
	v_mov_b32_e32 v19, v2
	v_mov_b32_e32 v20, v2
	v_mov_b32_e32 v21, v2
	v_mov_b32_e32 v22, v2
	v_mov_b32_e32 v23, v2
	v_mov_b32_e32 v24, v2
	v_mov_b32_e32 v25, v2
	v_mov_b32_e32 v34, v2
	v_mov_b32_e32 v35, v2
	v_mov_b32_e32 v36, v2
	v_mov_b32_e32 v37, v2
	v_mov_b32_e32 v38, v2
	v_mov_b32_e32 v39, v2
	v_mov_b32_e32 v40, v2
	v_mov_b32_e32 v41, v2
	v_mov_b32_e32 v50, v2
	v_mov_b32_e32 v51, v2
	v_mov_b32_e32 v52, v2
	v_mov_b32_e32 v53, v2
	v_mov_b32_e32 v54, v2
	v_mov_b32_e32 v55, v2
	v_mov_b32_e32 v56, v2
	v_mov_b32_e32 v57, v2
	v_mov_b32_e32 v10, v2
	v_mov_b32_e32 v11, v2
	v_mov_b32_e32 v12, v2
	v_mov_b32_e32 v13, v2
	v_mov_b32_e32 v14, v2
	v_mov_b32_e32 v15, v2
	v_mov_b32_e32 v16, v2
	v_mov_b32_e32 v17, v2
	v_mov_b32_e32 v26, v2
	v_mov_b32_e32 v27, v2
	v_mov_b32_e32 v28, v2
	v_mov_b32_e32 v29, v2
	v_mov_b32_e32 v30, v2
	v_mov_b32_e32 v31, v2
	v_mov_b32_e32 v32, v2
	v_mov_b32_e32 v33, v2
	v_mov_b32_e32 v42, v2
	v_mov_b32_e32 v43, v2
	v_mov_b32_e32 v44, v2
	v_mov_b32_e32 v45, v2
	v_mov_b32_e32 v46, v2
	v_mov_b32_e32 v47, v2
	v_mov_b32_e32 v48, v2
	v_mov_b32_e32 v49, v2
	v_mov_b32_e32 v58, v2
	v_mov_b32_e32 v59, v2
	v_mov_b32_e32 v60, v2
	v_mov_b32_e32 v61, v2
	v_mov_b32_e32 v62, v2
	v_mov_b32_e32 v63, v2
	v_mov_b32_e32 v64, v2
	v_mov_b32_e32 v65, v2
	v_mov_b32_e32 v66, v2
	v_mov_b32_e32 v67, v2
	v_mov_b32_e32 v68, v2
	v_mov_b32_e32 v69, v2
	v_mov_b32_e32 v70, v2
	v_mov_b32_e32 v71, v2
	v_mov_b32_e32 v72, v2
	v_mov_b32_e32 v73, v2
	v_mov_b32_e32 v82, v2
	v_mov_b32_e32 v83, v2
	v_mov_b32_e32 v84, v2
	v_mov_b32_e32 v85, v2
	v_mov_b32_e32 v86, v2
	v_mov_b32_e32 v87, v2
	v_mov_b32_e32 v88, v2
	v_mov_b32_e32 v89, v2
	v_mov_b32_e32 v98, v2
	v_mov_b32_e32 v99, v2
	v_mov_b32_e32 v100, v2
	v_mov_b32_e32 v101, v2
	v_mov_b32_e32 v102, v2
	v_mov_b32_e32 v103, v2
	v_mov_b32_e32 v104, v2
	v_mov_b32_e32 v105, v2
	v_mov_b32_e32 v122, v2
	v_mov_b32_e32 v123, v2
	v_mov_b32_e32 v124, v2
	v_mov_b32_e32 v125, v2
	v_mov_b32_e32 v126, v2
	v_mov_b32_e32 v127, v2
	v_mov_b32_e32 v128, v2
	v_mov_b32_e32 v129, v2
	v_mov_b32_e32 v74, v2
	v_mov_b32_e32 v75, v2
	v_mov_b32_e32 v76, v2
	v_mov_b32_e32 v77, v2
	v_mov_b32_e32 v78, v2
	v_mov_b32_e32 v79, v2
	v_mov_b32_e32 v80, v2
	v_mov_b32_e32 v81, v2
	v_mov_b32_e32 v90, v2
	v_mov_b32_e32 v91, v2
	v_mov_b32_e32 v92, v2
	v_mov_b32_e32 v93, v2
	v_mov_b32_e32 v94, v2
	v_mov_b32_e32 v95, v2
	v_mov_b32_e32 v96, v2
	v_mov_b32_e32 v97, v2
	v_mov_b32_e32 v132, v2
	v_mov_b32_e32 v133, v2
	v_mov_b32_e32 v134, v2
	v_mov_b32_e32 v135, v2
	v_mov_b32_e32 v136, v2
	v_mov_b32_e32 v137, v2
	v_mov_b32_e32 v138, v2
	v_mov_b32_e32 v139, v2
	v_mov_b32_e32 v140, v2
	v_mov_b32_e32 v141, v2
	v_mov_b32_e32 v142, v2
	v_mov_b32_e32 v143, v2
	v_mov_b32_e32 v144, v2
	v_mov_b32_e32 v145, v2
	v_mov_b32_e32 v146, v2
	v_mov_b32_e32 v147, v2
	v_add_u32_e32 v238, 0x10000, v210
.LBB0_1049:
	s_add_u32 s24, s16, 0x2fff00
	s_addc_u32 s25, s17, 0
	s_cmp_eq_u32 s61, 28
	s_cselect_b32 s30, s57, s24
	s_cselect_b32 s31, s11, s25
	s_cselect_b32 s28, s58, s59
	s_cselect_b32 s29, s9, s60
	s_add_u32 s24, s30, 0x300000
	s_addc_u32 s25, s31, 0
	s_add_i32 s62, 0, 0x10000
	s_add_i32 s68, 0, 0x14000
	ds_read_b128 v[106:109], v238
	ds_read_b128 v[110:113], v238 offset:1024
	ds_read_b128 v[114:117], v238 offset:2048
	ds_read_b128 v[118:121], v238 offset:3072
	ds_read_b128 v[148:151], v238 offset:16384
	ds_read_b128 v[152:155], v238 offset:17408
	ds_read_b128 v[156:159], v238 offset:18432
	ds_read_b128 v[160:163], v238 offset:19456
	ds_read_b64_tr_b16 v[164:165], v194 offset:0
	ds_read_b64_tr_b16 v[166:167], v195 offset:0
	ds_read_b64_tr_b16 v[182:183], v194 offset:0x2000
	ds_read_b64_tr_b16 v[184:185], v195 offset:0x2000
	ds_read_b64_tr_b16 v[186:187], v196 offset:0
	ds_read_b64_tr_b16 v[188:189], v197 offset:0
	ds_read_b64_tr_b16 v[190:191], v196 offset:0x2000
	ds_read_b64_tr_b16 v[192:193], v197 offset:0x2000
	ds_read_b64_tr_b16 v[222:223], v198 offset:0
	ds_read_b64_tr_b16 v[224:225], v199 offset:0
	ds_read_b64_tr_b16 v[226:227], v198 offset:0x2000
	ds_read_b64_tr_b16 v[228:229], v199 offset:0x2000
	ds_read_b64_tr_b16 v[230:231], v208 offset:0
	ds_read_b64_tr_b16 v[232:233], v209 offset:0
	ds_read_b64_tr_b16 v[234:235], v208 offset:0x2000
	ds_read_b64_tr_b16 v[236:237], v209 offset:0x2000
	s_add_i32 m0, s43, 0xc000
	s_nop 0
	global_load_lds_dwordx4 v180, s[16:17]
	s_add_i32 m0, s43, 0xe000
	s_nop 0
	global_load_lds_dwordx4 v178, s[16:17]
	s_waitcnt vmcnt(8)
	s_waitcnt lgkmcnt(0)
	s_barrier
	s_setprio 1
	s_waitcnt lgkmcnt(0)
	v_mfma_f32_16x16x32_bf16 v[144:147], v[106:109], v[164:167], v[144:147]
	v_mfma_f32_16x16x32_bf16 v[140:143], v[114:117], v[164:167], v[140:143]
	v_mfma_f32_16x16x32_bf16 v[136:139], v[106:109], v[186:189], v[136:139]
	v_mfma_f32_16x16x32_bf16 v[132:135], v[114:117], v[186:189], v[132:135]
	v_mfma_f32_16x16x32_bf16 v[94:97], v[106:109], v[222:225], v[94:97]
	v_mfma_f32_16x16x32_bf16 v[90:93], v[114:117], v[222:225], v[90:93]
	v_mfma_f32_16x16x32_bf16 v[78:81], v[106:109], v[230:233], v[78:81]
	v_mfma_f32_16x16x32_bf16 v[74:77], v[114:117], v[230:233], v[74:77]
	v_mfma_f32_16x16x32_bf16 v[144:147], v[110:113], v[182:185], v[144:147]
	v_mfma_f32_16x16x32_bf16 v[140:143], v[118:121], v[182:185], v[140:143]
	v_mfma_f32_16x16x32_bf16 v[136:139], v[110:113], v[190:193], v[136:139]
	v_mfma_f32_16x16x32_bf16 v[132:135], v[118:121], v[190:193], v[132:135]
	v_mfma_f32_16x16x32_bf16 v[94:97], v[110:113], v[226:229], v[94:97]
	v_mfma_f32_16x16x32_bf16 v[90:93], v[118:121], v[226:229], v[90:93]
	v_mfma_f32_16x16x32_bf16 v[78:81], v[110:113], v[234:237], v[78:81]
	v_mfma_f32_16x16x32_bf16 v[74:77], v[118:121], v[234:237], v[74:77]
	s_setprio 0
	s_setprio 1
	v_mfma_f32_16x16x32_bf16 v[126:129], v[148:151], v[164:167], v[126:129]
	v_mfma_f32_16x16x32_bf16 v[122:125], v[156:159], v[164:167], v[122:125]
	v_mfma_f32_16x16x32_bf16 v[102:105], v[148:151], v[186:189], v[102:105]
	v_mfma_f32_16x16x32_bf16 v[98:101], v[156:159], v[186:189], v[98:101]
	v_mfma_f32_16x16x32_bf16 v[86:89], v[148:151], v[222:225], v[86:89]
	v_mfma_f32_16x16x32_bf16 v[82:85], v[156:159], v[222:225], v[82:85]
	v_mfma_f32_16x16x32_bf16 v[70:73], v[148:151], v[230:233], v[70:73]
	v_mfma_f32_16x16x32_bf16 v[66:69], v[156:159], v[230:233], v[66:69]
	v_mfma_f32_16x16x32_bf16 v[126:129], v[152:155], v[182:185], v[126:129]
	v_mfma_f32_16x16x32_bf16 v[122:125], v[160:163], v[182:185], v[122:125]
	v_mfma_f32_16x16x32_bf16 v[102:105], v[152:155], v[190:193], v[102:105]
	v_mfma_f32_16x16x32_bf16 v[98:101], v[160:163], v[190:193], v[98:101]
	v_mfma_f32_16x16x32_bf16 v[86:89], v[152:155], v[226:229], v[86:89]
	v_mfma_f32_16x16x32_bf16 v[82:85], v[160:163], v[226:229], v[82:85]
	v_mfma_f32_16x16x32_bf16 v[70:73], v[152:155], v[234:237], v[70:73]
	v_mfma_f32_16x16x32_bf16 v[66:69], v[160:163], v[234:237], v[66:69]
	s_setprio 0
	s_barrier
	ds_read_b64_tr_b16 v[164:165], v194 offset:0x4000
	ds_read_b64_tr_b16 v[166:167], v195 offset:0x4000
	ds_read_b64_tr_b16 v[182:183], v194 offset:0x6000
	ds_read_b64_tr_b16 v[184:185], v195 offset:0x6000
	ds_read_b64_tr_b16 v[186:187], v196 offset:0x4000
	ds_read_b64_tr_b16 v[188:189], v197 offset:0x4000
	ds_read_b64_tr_b16 v[190:191], v196 offset:0x6000
	ds_read_b64_tr_b16 v[192:193], v197 offset:0x6000
	ds_read_b64_tr_b16 v[222:223], v198 offset:0x4000
	ds_read_b64_tr_b16 v[224:225], v199 offset:0x4000
	ds_read_b64_tr_b16 v[226:227], v198 offset:0x6000
	ds_read_b64_tr_b16 v[228:229], v199 offset:0x6000
	ds_read_b64_tr_b16 v[230:231], v208 offset:0x4000
	ds_read_b64_tr_b16 v[232:233], v209 offset:0x4000
	ds_read_b64_tr_b16 v[234:235], v208 offset:0x6000
	s_add_i32 s62, s62, s42
	ds_read_b64_tr_b16 v[236:237], v209 offset:0x6000
	s_add_u32 s100, s28, s34
	s_addc_u32 s101, s29, s35
	s_mov_b32 m0, s62
	s_nop 0
	global_load_lds_dwordx4 v130, s[28:29]
	s_add_i32 m0, s62, 0x2000
	s_add_u32 s62, s28, 0x80000
	s_addc_u32 s63, s29, 0
	s_add_i32 s68, s68, s42
	global_load_lds_dwordx4 v170, s[28:29]
	s_mov_b32 m0, s68
	s_nop 0
	global_load_lds_dwordx4 v130, s[62:63]
	s_add_i32 m0, s68, 0x2000
	s_nop 0
	global_load_lds_dwordx4 v170, s[62:63]
	s_add_u32 s98, s30, s82
	s_addc_u32 s99, s31, s83
	s_mov_b32 m0, s43
	s_nop 0
	global_load_lds_dwordx4 v176, s[30:31]
	s_mov_b32 m0, s44
	s_nop 0
	global_load_lds_dwordx4 v168, s[30:31]
	s_waitcnt vmcnt(8)
	s_waitcnt lgkmcnt(0)
	s_barrier
	s_setprio 1
	v_mfma_f32_16x16x32_bf16 v[62:65], v[106:109], v[164:167], v[62:65]
	v_mfma_f32_16x16x32_bf16 v[58:61], v[114:117], v[164:167], v[58:61]
	v_mfma_f32_16x16x32_bf16 v[46:49], v[106:109], v[186:189], v[46:49]
	v_mfma_f32_16x16x32_bf16 v[42:45], v[114:117], v[186:189], v[42:45]
	v_mfma_f32_16x16x32_bf16 v[30:33], v[106:109], v[222:225], v[30:33]
	v_mfma_f32_16x16x32_bf16 v[26:29], v[114:117], v[222:225], v[26:29]
	v_mfma_f32_16x16x32_bf16 v[14:17], v[106:109], v[230:233], v[14:17]
	v_mfma_f32_16x16x32_bf16 v[10:13], v[114:117], v[230:233], v[10:13]
	v_mfma_f32_16x16x32_bf16 v[62:65], v[110:113], v[182:185], v[62:65]
	v_mfma_f32_16x16x32_bf16 v[58:61], v[118:121], v[182:185], v[58:61]
	v_mfma_f32_16x16x32_bf16 v[46:49], v[110:113], v[190:193], v[46:49]
	v_mfma_f32_16x16x32_bf16 v[42:45], v[118:121], v[190:193], v[42:45]
	v_mfma_f32_16x16x32_bf16 v[30:33], v[110:113], v[226:229], v[30:33]
	v_mfma_f32_16x16x32_bf16 v[26:29], v[118:121], v[226:229], v[26:29]
	v_mfma_f32_16x16x32_bf16 v[14:17], v[110:113], v[234:237], v[14:17]
	v_mfma_f32_16x16x32_bf16 v[10:13], v[118:121], v[234:237], v[10:13]
	s_setprio 0
	s_setprio 1
	v_mfma_f32_16x16x32_bf16 v[54:57], v[148:151], v[164:167], v[54:57]
	v_mfma_f32_16x16x32_bf16 v[50:53], v[156:159], v[164:167], v[50:53]
	v_mfma_f32_16x16x32_bf16 v[38:41], v[148:151], v[186:189], v[38:41]
	v_mfma_f32_16x16x32_bf16 v[34:37], v[156:159], v[186:189], v[34:37]
	v_mfma_f32_16x16x32_bf16 v[22:25], v[148:151], v[222:225], v[22:25]
	v_mfma_f32_16x16x32_bf16 v[18:21], v[156:159], v[222:225], v[18:21]
	v_mfma_f32_16x16x32_bf16 v[6:9], v[148:151], v[230:233], v[6:9]
	v_mfma_f32_16x16x32_bf16 v[2:5], v[156:159], v[230:233], v[2:5]
	v_mfma_f32_16x16x32_bf16 v[54:57], v[152:155], v[182:185], v[54:57]
	v_mfma_f32_16x16x32_bf16 v[50:53], v[160:163], v[182:185], v[50:53]
	v_mfma_f32_16x16x32_bf16 v[38:41], v[152:155], v[190:193], v[38:41]
	v_mfma_f32_16x16x32_bf16 v[34:37], v[160:163], v[190:193], v[34:37]
	v_mfma_f32_16x16x32_bf16 v[22:25], v[152:155], v[226:229], v[22:25]
	v_mfma_f32_16x16x32_bf16 v[18:21], v[160:163], v[226:229], v[18:21]
	v_mfma_f32_16x16x32_bf16 v[6:9], v[152:155], v[234:237], v[6:9]
	v_mfma_f32_16x16x32_bf16 v[2:5], v[160:163], v[234:237], v[2:5]
	s_setprio 0
	s_barrier
	s_add_i32 s30, 0, 0x18000
	s_add_i32 s31, 0, 0x1c000
	ds_read_b128 v[106:109], v238 offset:32768
	ds_read_b128 v[110:113], v238 offset:33792
	ds_read_b128 v[114:117], v238 offset:34816
	ds_read_b128 v[118:121], v238 offset:35840
	ds_read_b128 v[148:151], v238 offset:49152
	ds_read_b128 v[152:155], v238 offset:50176
	ds_read_b128 v[156:159], v238 offset:51200
	ds_read_b128 v[160:163], v238 offset:52224
	ds_read_b64_tr_b16 v[164:165], v194 offset:0x8000
	ds_read_b64_tr_b16 v[166:167], v195 offset:0x8000
	ds_read_b64_tr_b16 v[182:183], v194 offset:0xa000
	ds_read_b64_tr_b16 v[184:185], v195 offset:0xa000
	ds_read_b64_tr_b16 v[186:187], v196 offset:0x8000
	ds_read_b64_tr_b16 v[188:189], v197 offset:0x8000
	ds_read_b64_tr_b16 v[190:191], v196 offset:0xa000
	ds_read_b64_tr_b16 v[192:193], v197 offset:0xa000
	ds_read_b64_tr_b16 v[222:223], v198 offset:0x8000
	ds_read_b64_tr_b16 v[224:225], v199 offset:0x8000
	ds_read_b64_tr_b16 v[226:227], v198 offset:0xa000
	ds_read_b64_tr_b16 v[228:229], v199 offset:0xa000
	ds_read_b64_tr_b16 v[230:231], v208 offset:0x8000
	ds_read_b64_tr_b16 v[232:233], v209 offset:0x8000
	ds_read_b64_tr_b16 v[234:235], v208 offset:0xa000
	s_mov_b32 m0, s45
	ds_read_b64_tr_b16 v[236:237], v209 offset:0xa000
	global_load_lds_dwordx4 v176, s[98:99]
	s_mov_b32 m0, s46
	s_nop 0
	global_load_lds_dwordx4 v168, s[98:99]
	s_waitcnt vmcnt(8)
	s_waitcnt lgkmcnt(0)
	s_barrier
	s_setprio 1
	s_waitcnt lgkmcnt(0)
	v_mfma_f32_16x16x32_bf16 v[144:147], v[106:109], v[164:167], v[144:147]
	v_mfma_f32_16x16x32_bf16 v[140:143], v[114:117], v[164:167], v[140:143]
	v_mfma_f32_16x16x32_bf16 v[136:139], v[106:109], v[186:189], v[136:139]
	v_mfma_f32_16x16x32_bf16 v[132:135], v[114:117], v[186:189], v[132:135]
	v_mfma_f32_16x16x32_bf16 v[94:97], v[106:109], v[222:225], v[94:97]
	v_mfma_f32_16x16x32_bf16 v[90:93], v[114:117], v[222:225], v[90:93]
	v_mfma_f32_16x16x32_bf16 v[78:81], v[106:109], v[230:233], v[78:81]
	v_mfma_f32_16x16x32_bf16 v[74:77], v[114:117], v[230:233], v[74:77]
	v_mfma_f32_16x16x32_bf16 v[144:147], v[110:113], v[182:185], v[144:147]
	v_mfma_f32_16x16x32_bf16 v[140:143], v[118:121], v[182:185], v[140:143]
	v_mfma_f32_16x16x32_bf16 v[136:139], v[110:113], v[190:193], v[136:139]
	v_mfma_f32_16x16x32_bf16 v[132:135], v[118:121], v[190:193], v[132:135]
	v_mfma_f32_16x16x32_bf16 v[94:97], v[110:113], v[226:229], v[94:97]
	v_mfma_f32_16x16x32_bf16 v[90:93], v[118:121], v[226:229], v[90:93]
	v_mfma_f32_16x16x32_bf16 v[78:81], v[110:113], v[234:237], v[78:81]
	v_mfma_f32_16x16x32_bf16 v[74:77], v[118:121], v[234:237], v[74:77]
	s_setprio 0
	s_setprio 1
	v_mfma_f32_16x16x32_bf16 v[126:129], v[148:151], v[164:167], v[126:129]
	v_mfma_f32_16x16x32_bf16 v[122:125], v[156:159], v[164:167], v[122:125]
	v_mfma_f32_16x16x32_bf16 v[102:105], v[148:151], v[186:189], v[102:105]
	v_mfma_f32_16x16x32_bf16 v[98:101], v[156:159], v[186:189], v[98:101]
	v_mfma_f32_16x16x32_bf16 v[86:89], v[148:151], v[222:225], v[86:89]
	v_mfma_f32_16x16x32_bf16 v[82:85], v[156:159], v[222:225], v[82:85]
	v_mfma_f32_16x16x32_bf16 v[70:73], v[148:151], v[230:233], v[70:73]
	v_mfma_f32_16x16x32_bf16 v[66:69], v[156:159], v[230:233], v[66:69]
	v_mfma_f32_16x16x32_bf16 v[126:129], v[152:155], v[182:185], v[126:129]
	v_mfma_f32_16x16x32_bf16 v[122:125], v[160:163], v[182:185], v[122:125]
	v_mfma_f32_16x16x32_bf16 v[102:105], v[152:155], v[190:193], v[102:105]
	v_mfma_f32_16x16x32_bf16 v[98:101], v[160:163], v[190:193], v[98:101]
	v_mfma_f32_16x16x32_bf16 v[86:89], v[152:155], v[226:229], v[86:89]
	v_mfma_f32_16x16x32_bf16 v[82:85], v[160:163], v[226:229], v[82:85]
	v_mfma_f32_16x16x32_bf16 v[70:73], v[152:155], v[234:237], v[70:73]
	v_mfma_f32_16x16x32_bf16 v[66:69], v[160:163], v[234:237], v[66:69]
	s_setprio 0
	s_barrier
	ds_read_b64_tr_b16 v[164:165], v194 offset:0xc000
	ds_read_b64_tr_b16 v[166:167], v195 offset:0xc000
	ds_read_b64_tr_b16 v[182:183], v194 offset:0xe000
	ds_read_b64_tr_b16 v[184:185], v195 offset:0xe000
	ds_read_b64_tr_b16 v[186:187], v196 offset:0xc000
	ds_read_b64_tr_b16 v[188:189], v197 offset:0xc000
	ds_read_b64_tr_b16 v[190:191], v196 offset:0xe000
	ds_read_b64_tr_b16 v[192:193], v197 offset:0xe000
	ds_read_b64_tr_b16 v[222:223], v198 offset:0xc000
	ds_read_b64_tr_b16 v[224:225], v199 offset:0xc000
	ds_read_b64_tr_b16 v[226:227], v198 offset:0xe000
	ds_read_b64_tr_b16 v[228:229], v199 offset:0xe000
	ds_read_b64_tr_b16 v[230:231], v208 offset:0xc000
	ds_read_b64_tr_b16 v[232:233], v209 offset:0xc000
	ds_read_b64_tr_b16 v[234:235], v208 offset:0xe000
	s_add_i32 s30, s30, s42
	ds_read_b64_tr_b16 v[236:237], v209 offset:0xe000
	s_mov_b32 m0, s30
	s_nop 0
	global_load_lds_dwordx4 v130, s[100:101]
	s_add_i32 m0, s30, 0x2000
	s_add_u32 s28, s28, 0x80080
	s_addc_u32 s29, s29, 0
	s_add_i32 s30, s31, s42
	global_load_lds_dwordx4 v170, s[100:101]
	s_mov_b32 m0, s30
	s_nop 0
	global_load_lds_dwordx4 v130, s[28:29]
	s_add_i32 m0, s30, 0x2000
	s_nop 0
	global_load_lds_dwordx4 v170, s[28:29]
	s_mov_b32 m0, s48
	s_nop 0
	global_load_lds_dwordx4 v176, s[24:25]
	s_mov_b32 m0, s49
	s_nop 0
	global_load_lds_dwordx4 v168, s[24:25]
	s_waitcnt vmcnt(8)
	s_waitcnt lgkmcnt(0)
	s_barrier
	s_setprio 1
	v_mfma_f32_16x16x32_bf16 v[62:65], v[106:109], v[164:167], v[62:65]
	v_mfma_f32_16x16x32_bf16 v[58:61], v[114:117], v[164:167], v[58:61]
	v_mfma_f32_16x16x32_bf16 v[46:49], v[106:109], v[186:189], v[46:49]
	v_mfma_f32_16x16x32_bf16 v[42:45], v[114:117], v[186:189], v[42:45]
	v_mfma_f32_16x16x32_bf16 v[30:33], v[106:109], v[222:225], v[30:33]
	v_mfma_f32_16x16x32_bf16 v[26:29], v[114:117], v[222:225], v[26:29]
	v_mfma_f32_16x16x32_bf16 v[14:17], v[106:109], v[230:233], v[14:17]
	v_mfma_f32_16x16x32_bf16 v[10:13], v[114:117], v[230:233], v[10:13]
	v_mfma_f32_16x16x32_bf16 v[62:65], v[110:113], v[182:185], v[62:65]
	v_mfma_f32_16x16x32_bf16 v[58:61], v[118:121], v[182:185], v[58:61]
	v_mfma_f32_16x16x32_bf16 v[46:49], v[110:113], v[190:193], v[46:49]
	v_mfma_f32_16x16x32_bf16 v[42:45], v[118:121], v[190:193], v[42:45]
	v_mfma_f32_16x16x32_bf16 v[30:33], v[110:113], v[226:229], v[30:33]
	v_mfma_f32_16x16x32_bf16 v[26:29], v[118:121], v[226:229], v[26:29]
	v_mfma_f32_16x16x32_bf16 v[14:17], v[110:113], v[234:237], v[14:17]
	v_mfma_f32_16x16x32_bf16 v[10:13], v[118:121], v[234:237], v[10:13]
	s_setprio 0
	s_setprio 1
	v_mfma_f32_16x16x32_bf16 v[54:57], v[148:151], v[164:167], v[54:57]
	v_mfma_f32_16x16x32_bf16 v[50:53], v[156:159], v[164:167], v[50:53]
	v_mfma_f32_16x16x32_bf16 v[38:41], v[148:151], v[186:189], v[38:41]
	v_mfma_f32_16x16x32_bf16 v[34:37], v[156:159], v[186:189], v[34:37]
	v_mfma_f32_16x16x32_bf16 v[22:25], v[148:151], v[222:225], v[22:25]
	v_mfma_f32_16x16x32_bf16 v[18:21], v[156:159], v[222:225], v[18:21]
	v_mfma_f32_16x16x32_bf16 v[6:9], v[148:151], v[230:233], v[6:9]
	v_mfma_f32_16x16x32_bf16 v[2:5], v[156:159], v[230:233], v[2:5]
	v_mfma_f32_16x16x32_bf16 v[54:57], v[152:155], v[182:185], v[54:57]
	v_mfma_f32_16x16x32_bf16 v[50:53], v[160:163], v[182:185], v[50:53]
	v_mfma_f32_16x16x32_bf16 v[38:41], v[152:155], v[190:193], v[38:41]
	v_mfma_f32_16x16x32_bf16 v[34:37], v[160:163], v[190:193], v[34:37]
	v_mfma_f32_16x16x32_bf16 v[22:25], v[152:155], v[226:229], v[22:25]
	v_mfma_f32_16x16x32_bf16 v[18:21], v[160:163], v[226:229], v[18:21]
	v_mfma_f32_16x16x32_bf16 v[6:9], v[152:155], v[234:237], v[6:9]
	v_mfma_f32_16x16x32_bf16 v[2:5], v[160:163], v[234:237], v[2:5]
	s_setprio 0
	s_barrier
	s_add_i32 s61, s61, 2
	s_add_u32 s59, s59, 0x100
	s_addc_u32 s60, s60, 0
	s_add_u32 s16, s16, 0x600000
	s_addc_u32 s17, s17, 0
	s_cmp_gt_u32 s61, 29
	s_cbranch_scc0 .LBB0_1049
	s_and_b64 vcc, exec, s[6:7]
	s_cbranch_vccz .LBB0_1052
	s_barrier

.LBB0_1187:
	s_ashr_i32 s9, s8, 31
	s_lshl_b64 s[10:11], s[8:9], 20
	s_add_u32 s10, s28, s10
	s_addc_u32 s11, s29, s11
	s_and_b64 s[12:13], s[0:1], exec
	s_cselect_b32 s9, s11, s17
	s_cselect_b32 s55, s10, s16
	s_ashr_i32 s7, s6, 31
	s_lshl_b64 s[12:13], s[6:7], 20
	s_add_u32 s12, s30, s12
	s_addc_u32 s13, s31, s13
	s_and_b64 s[24:25], s[0:1], exec
	s_cselect_b32 s7, s13, s15
	s_cselect_b32 s56, s12, s14
	s_add_u32 s57, s14, 0x100
	s_addc_u32 s58, s15, 0
	s_add_u32 s14, s16, 0x80080
	v_mov_b32_e32 v2, 0
	s_addc_u32 s15, s17, 0
	s_mov_b32 s59, -2
	v_mov_b32_e32 v3, v2
	v_mov_b32_e32 v4, v2
	v_mov_b32_e32 v5, v2
	v_mov_b32_e32 v10, v2
	v_mov_b32_e32 v11, v2
	v_mov_b32_e32 v12, v2
	v_mov_b32_e32 v13, v2
	v_mov_b32_e32 v18, v2
	v_mov_b32_e32 v19, v2
	v_mov_b32_e32 v20, v2
	v_mov_b32_e32 v21, v2
	v_mov_b32_e32 v26, v2
	v_mov_b32_e32 v27, v2
	v_mov_b32_e32 v28, v2
	v_mov_b32_e32 v29, v2
	v_mov_b32_e32 v34, v2
	v_mov_b32_e32 v35, v2
	v_mov_b32_e32 v36, v2
	v_mov_b32_e32 v37, v2
	v_mov_b32_e32 v42, v2
	v_mov_b32_e32 v43, v2
	v_mov_b32_e32 v44, v2
	v_mov_b32_e32 v45, v2
	v_mov_b32_e32 v50, v2
	v_mov_b32_e32 v51, v2
	v_mov_b32_e32 v52, v2
	v_mov_b32_e32 v53, v2
	v_mov_b32_e32 v58, v2
	v_mov_b32_e32 v59, v2
	v_mov_b32_e32 v60, v2
	v_mov_b32_e32 v61, v2
	v_mov_b32_e32 v6, v2
	v_mov_b32_e32 v7, v2
	v_mov_b32_e32 v8, v2
	v_mov_b32_e32 v9, v2
	v_mov_b32_e32 v14, v2
	v_mov_b32_e32 v15, v2
	v_mov_b32_e32 v16, v2
	v_mov_b32_e32 v17, v2
	v_mov_b32_e32 v22, v2
	v_mov_b32_e32 v23, v2
	v_mov_b32_e32 v24, v2
	v_mov_b32_e32 v25, v2
	v_mov_b32_e32 v30, v2
	v_mov_b32_e32 v31, v2
	v_mov_b32_e32 v32, v2
	v_mov_b32_e32 v33, v2
	v_mov_b32_e32 v38, v2
	v_mov_b32_e32 v39, v2
	v_mov_b32_e32 v40, v2
	v_mov_b32_e32 v41, v2
	v_mov_b32_e32 v46, v2
	v_mov_b32_e32 v47, v2
	v_mov_b32_e32 v48, v2
	v_mov_b32_e32 v49, v2
	v_mov_b32_e32 v54, v2
	v_mov_b32_e32 v55, v2
	v_mov_b32_e32 v56, v2
	v_mov_b32_e32 v57, v2
	v_mov_b32_e32 v62, v2
	v_mov_b32_e32 v63, v2
	v_mov_b32_e32 v64, v2
	v_mov_b32_e32 v65, v2
	v_mov_b32_e32 v66, v2
	v_mov_b32_e32 v67, v2
	v_mov_b32_e32 v68, v2
	v_mov_b32_e32 v69, v2
	v_mov_b32_e32 v74, v2
	v_mov_b32_e32 v75, v2
	v_mov_b32_e32 v76, v2
	v_mov_b32_e32 v77, v2
	v_mov_b32_e32 v82, v2
	v_mov_b32_e32 v83, v2
	v_mov_b32_e32 v84, v2
	v_mov_b32_e32 v85, v2
	v_mov_b32_e32 v90, v2
	v_mov_b32_e32 v91, v2
	v_mov_b32_e32 v92, v2
	v_mov_b32_e32 v93, v2
	v_mov_b32_e32 v98, v2
	v_mov_b32_e32 v99, v2
	v_mov_b32_e32 v100, v2
	v_mov_b32_e32 v101, v2
	v_mov_b32_e32 v106, v2
	v_mov_b32_e32 v107, v2
	v_mov_b32_e32 v108, v2
	v_mov_b32_e32 v109, v2
	v_mov_b32_e32 v114, v2
	v_mov_b32_e32 v115, v2
	v_mov_b32_e32 v116, v2
	v_mov_b32_e32 v117, v2
	v_mov_b32_e32 v122, v2
	v_mov_b32_e32 v123, v2
	v_mov_b32_e32 v124, v2
	v_mov_b32_e32 v125, v2
	v_mov_b32_e32 v70, v2
	v_mov_b32_e32 v71, v2
	v_mov_b32_e32 v72, v2
	v_mov_b32_e32 v73, v2
	v_mov_b32_e32 v78, v2
	v_mov_b32_e32 v79, v2
	v_mov_b32_e32 v80, v2
	v_mov_b32_e32 v81, v2
	v_mov_b32_e32 v86, v2
	v_mov_b32_e32 v87, v2
	v_mov_b32_e32 v88, v2
	v_mov_b32_e32 v89, v2
	v_mov_b32_e32 v94, v2
	v_mov_b32_e32 v95, v2
	v_mov_b32_e32 v96, v2
	v_mov_b32_e32 v97, v2
	v_mov_b32_e32 v102, v2
	v_mov_b32_e32 v103, v2
	v_mov_b32_e32 v104, v2
	v_mov_b32_e32 v105, v2
	v_mov_b32_e32 v110, v2
	v_mov_b32_e32 v111, v2
	v_mov_b32_e32 v112, v2
	v_mov_b32_e32 v113, v2
	v_mov_b32_e32 v118, v2
	v_mov_b32_e32 v119, v2
	v_mov_b32_e32 v120, v2
	v_mov_b32_e32 v121, v2
	v_mov_b32_e32 v126, v2
	v_mov_b32_e32 v127, v2
	v_mov_b32_e32 v128, v2
	v_mov_b32_e32 v129, v2
	v_add_u32_e32 v212, 0x10000, v160
.LBB0_1188:
	s_add_u32 s16, s14, 0xfff80080
	s_addc_u32 s17, s15, -1
	s_add_i32 s60, 0, 0x10000
	s_cmp_eq_u32 s59, 28
	s_cselect_b32 s25, s9, s17
	s_cselect_b32 s24, s55, s16
	s_cselect_b32 s17, s7, s58
	s_cselect_b32 s16, s56, s57
	s_add_i32 s62, 0, 0x14000
	ds_read_b128 v[162:165], v212
	ds_read_b128 v[166:169], v212 offset:1024
	ds_read_b128 v[176:179], v212 offset:2048
	ds_read_b128 v[180:183], v212 offset:3072
	ds_read_b128 v[184:187], v212 offset:16384
	ds_read_b128 v[188:191], v212 offset:17408
	ds_read_b128 v[192:195], v212 offset:18432
	ds_read_b128 v[196:199], v212 offset:19456
	s_add_i32 m0, s37, 0xc000
	ds_read_b128 v[208:211], v161
	ds_read_b128 v[222:225], v161 offset:1024
	ds_read_b128 v[226:229], v161 offset:2048
	ds_read_b128 v[230:233], v161 offset:3072
	ds_read_b128 v[234:237], v161 offset:4096
	ds_read_b128 v[238:241], v161 offset:5120
	ds_read_b128 v[242:245], v161 offset:6144
	ds_read_b128 v[246:249], v161 offset:7168
	global_load_lds_dwordx4 v158, s[14:15]
	s_add_i32 m0, s37, 0xe000
	s_nop 0
	global_load_lds_dwordx4 v156, s[14:15]
	s_waitcnt vmcnt(8)
	s_waitcnt lgkmcnt(0)
	s_barrier
	s_setprio 1
	s_waitcnt lgkmcnt(0)
	v_mfma_f32_16x16x32_bf16 v[126:129], v[162:165], v[208:211], v[126:129]
	v_mfma_f32_16x16x32_bf16 v[118:121], v[176:179], v[208:211], v[118:121]
	v_mfma_f32_16x16x32_bf16 v[110:113], v[162:165], v[226:229], v[110:113]
	v_mfma_f32_16x16x32_bf16 v[102:105], v[176:179], v[226:229], v[102:105]
	v_mfma_f32_16x16x32_bf16 v[94:97], v[162:165], v[234:237], v[94:97]
	v_mfma_f32_16x16x32_bf16 v[86:89], v[176:179], v[234:237], v[86:89]
	v_mfma_f32_16x16x32_bf16 v[78:81], v[162:165], v[242:245], v[78:81]
	v_mfma_f32_16x16x32_bf16 v[70:73], v[176:179], v[242:245], v[70:73]
	v_mfma_f32_16x16x32_bf16 v[126:129], v[166:169], v[222:225], v[126:129]
	v_mfma_f32_16x16x32_bf16 v[118:121], v[180:183], v[222:225], v[118:121]
	v_mfma_f32_16x16x32_bf16 v[110:113], v[166:169], v[230:233], v[110:113]
	v_mfma_f32_16x16x32_bf16 v[102:105], v[180:183], v[230:233], v[102:105]
	v_mfma_f32_16x16x32_bf16 v[94:97], v[166:169], v[238:241], v[94:97]
	v_mfma_f32_16x16x32_bf16 v[86:89], v[180:183], v[238:241], v[86:89]
	v_mfma_f32_16x16x32_bf16 v[78:81], v[166:169], v[246:249], v[78:81]
	v_mfma_f32_16x16x32_bf16 v[70:73], v[180:183], v[246:249], v[70:73]
	s_setprio 0
	s_setprio 1
	v_mfma_f32_16x16x32_bf16 v[122:125], v[184:187], v[208:211], v[122:125]
	v_mfma_f32_16x16x32_bf16 v[114:117], v[192:195], v[208:211], v[114:117]
	v_mfma_f32_16x16x32_bf16 v[106:109], v[184:187], v[226:229], v[106:109]
	v_mfma_f32_16x16x32_bf16 v[98:101], v[192:195], v[226:229], v[98:101]
	v_mfma_f32_16x16x32_bf16 v[90:93], v[184:187], v[234:237], v[90:93]
	v_mfma_f32_16x16x32_bf16 v[82:85], v[192:195], v[234:237], v[82:85]
	v_mfma_f32_16x16x32_bf16 v[74:77], v[184:187], v[242:245], v[74:77]
	v_mfma_f32_16x16x32_bf16 v[66:69], v[192:195], v[242:245], v[66:69]
	v_mfma_f32_16x16x32_bf16 v[122:125], v[188:191], v[222:225], v[122:125]
	v_mfma_f32_16x16x32_bf16 v[114:117], v[196:199], v[222:225], v[114:117]
	v_mfma_f32_16x16x32_bf16 v[106:109], v[188:191], v[230:233], v[106:109]
	v_mfma_f32_16x16x32_bf16 v[98:101], v[196:199], v[230:233], v[98:101]
	v_mfma_f32_16x16x32_bf16 v[90:93], v[188:191], v[238:241], v[90:93]
	v_mfma_f32_16x16x32_bf16 v[82:85], v[196:199], v[238:241], v[82:85]
	v_mfma_f32_16x16x32_bf16 v[74:77], v[188:191], v[246:249], v[74:77]
	v_mfma_f32_16x16x32_bf16 v[66:69], v[196:199], v[246:249], v[66:69]
	s_setprio 0
	s_barrier
	s_add_i32 s60, s60, s36
	s_add_u32 s98, s16, s34
	s_addc_u32 s99, s17, s35
	s_mov_b32 m0, s60
	ds_read_b128 v[208:211], v161 offset:16384
	ds_read_b128 v[222:225], v161 offset:17408
	ds_read_b128 v[226:229], v161 offset:18432
	ds_read_b128 v[230:233], v161 offset:19456
	ds_read_b128 v[234:237], v161 offset:20480
	ds_read_b128 v[238:241], v161 offset:21504
	ds_read_b128 v[242:245], v161 offset:22528
	ds_read_b128 v[246:249], v161 offset:23552
	global_load_lds_dwordx4 v136, s[16:17]
	s_add_i32 m0, s60, 0x2000
	s_add_u32 s60, s16, 0x80000
	s_addc_u32 s61, s17, 0
	s_add_i32 s62, s62, s36
	global_load_lds_dwordx4 v132, s[16:17]
	s_mov_b32 m0, s62
	s_nop 0
	global_load_lds_dwordx4 v136, s[60:61]
	s_add_i32 m0, s62, 0x2000
	s_nop 0
	global_load_lds_dwordx4 v132, s[60:61]
	s_add_u32 s100, s24, s34
	s_addc_u32 s101, s25, s35
	s_mov_b32 m0, s37
	s_nop 0
	global_load_lds_dwordx4 v138, s[24:25]
	s_mov_b32 m0, s38
	s_nop 0
	global_load_lds_dwordx4 v134, s[24:25]
	s_waitcnt vmcnt(8)
	s_waitcnt lgkmcnt(0)
	s_barrier
	s_setprio 1
	s_waitcnt lgkmcnt(0)
	v_mfma_f32_16x16x32_bf16 v[62:65], v[162:165], v[208:211], v[62:65]
	v_mfma_f32_16x16x32_bf16 v[54:57], v[176:179], v[208:211], v[54:57]
	v_mfma_f32_16x16x32_bf16 v[46:49], v[162:165], v[226:229], v[46:49]
	v_mfma_f32_16x16x32_bf16 v[38:41], v[176:179], v[226:229], v[38:41]
	v_mfma_f32_16x16x32_bf16 v[30:33], v[162:165], v[234:237], v[30:33]
	v_mfma_f32_16x16x32_bf16 v[22:25], v[176:179], v[234:237], v[22:25]
	v_mfma_f32_16x16x32_bf16 v[14:17], v[162:165], v[242:245], v[14:17]
	v_mfma_f32_16x16x32_bf16 v[6:9], v[176:179], v[242:245], v[6:9]
	v_mfma_f32_16x16x32_bf16 v[62:65], v[166:169], v[222:225], v[62:65]
	v_mfma_f32_16x16x32_bf16 v[54:57], v[180:183], v[222:225], v[54:57]
	v_mfma_f32_16x16x32_bf16 v[46:49], v[166:169], v[230:233], v[46:49]
	v_mfma_f32_16x16x32_bf16 v[38:41], v[180:183], v[230:233], v[38:41]
	v_mfma_f32_16x16x32_bf16 v[30:33], v[166:169], v[238:241], v[30:33]
	v_mfma_f32_16x16x32_bf16 v[22:25], v[180:183], v[238:241], v[22:25]
	v_mfma_f32_16x16x32_bf16 v[14:17], v[166:169], v[246:249], v[14:17]
	v_mfma_f32_16x16x32_bf16 v[6:9], v[180:183], v[246:249], v[6:9]
	s_setprio 0
	s_setprio 1
	v_mfma_f32_16x16x32_bf16 v[58:61], v[184:187], v[208:211], v[58:61]
	v_mfma_f32_16x16x32_bf16 v[50:53], v[192:195], v[208:211], v[50:53]
	v_mfma_f32_16x16x32_bf16 v[42:45], v[184:187], v[226:229], v[42:45]
	v_mfma_f32_16x16x32_bf16 v[34:37], v[192:195], v[226:229], v[34:37]
	v_mfma_f32_16x16x32_bf16 v[26:29], v[184:187], v[234:237], v[26:29]
	v_mfma_f32_16x16x32_bf16 v[18:21], v[192:195], v[234:237], v[18:21]
	v_mfma_f32_16x16x32_bf16 v[10:13], v[184:187], v[242:245], v[10:13]
	v_mfma_f32_16x16x32_bf16 v[2:5], v[192:195], v[242:245], v[2:5]
	v_mfma_f32_16x16x32_bf16 v[58:61], v[188:191], v[222:225], v[58:61]
	v_mfma_f32_16x16x32_bf16 v[50:53], v[196:199], v[222:225], v[50:53]
	v_mfma_f32_16x16x32_bf16 v[42:45], v[188:191], v[230:233], v[42:45]
	v_mfma_f32_16x16x32_bf16 v[34:37], v[196:199], v[230:233], v[34:37]
	v_mfma_f32_16x16x32_bf16 v[26:29], v[188:191], v[238:241], v[26:29]
	v_mfma_f32_16x16x32_bf16 v[18:21], v[196:199], v[238:241], v[18:21]
	v_mfma_f32_16x16x32_bf16 v[10:13], v[188:191], v[246:249], v[10:13]
	v_mfma_f32_16x16x32_bf16 v[2:5], v[196:199], v[246:249], v[2:5]
	s_setprio 0
	s_barrier
	s_add_i32 s60, 0, 0x18000
	s_add_i32 s61, 0, 0x1c000
	ds_read_b128 v[162:165], v212 offset:32768
	ds_read_b128 v[166:169], v212 offset:33792
	ds_read_b128 v[176:179], v212 offset:34816
	ds_read_b128 v[180:183], v212 offset:35840
	ds_read_b128 v[184:187], v212 offset:49152
	ds_read_b128 v[188:191], v212 offset:50176
	ds_read_b128 v[192:195], v212 offset:51200
	ds_read_b128 v[196:199], v212 offset:52224
	s_add_u32 s24, s24, 0x80000
	s_addc_u32 s25, s25, 0
	s_mov_b32 m0, s39
	ds_read_b128 v[208:211], v161 offset:32768
	ds_read_b128 v[222:225], v161 offset:33792
	ds_read_b128 v[226:229], v161 offset:34816
	ds_read_b128 v[230:233], v161 offset:35840
	ds_read_b128 v[234:237], v161 offset:36864
	ds_read_b128 v[238:241], v161 offset:37888
	ds_read_b128 v[242:245], v161 offset:38912
	ds_read_b128 v[246:249], v161 offset:39936
	global_load_lds_dwordx4 v138, s[24:25]
	s_mov_b32 m0, s40
	s_nop 0
	global_load_lds_dwordx4 v134, s[24:25]
	s_waitcnt vmcnt(8)
	s_waitcnt lgkmcnt(0)
	s_barrier
	s_setprio 1
	s_waitcnt lgkmcnt(0)
	v_mfma_f32_16x16x32_bf16 v[126:129], v[162:165], v[208:211], v[126:129]
	v_mfma_f32_16x16x32_bf16 v[118:121], v[176:179], v[208:211], v[118:121]
	v_mfma_f32_16x16x32_bf16 v[110:113], v[162:165], v[226:229], v[110:113]
	v_mfma_f32_16x16x32_bf16 v[102:105], v[176:179], v[226:229], v[102:105]
	v_mfma_f32_16x16x32_bf16 v[94:97], v[162:165], v[234:237], v[94:97]
	v_mfma_f32_16x16x32_bf16 v[86:89], v[176:179], v[234:237], v[86:89]
	v_mfma_f32_16x16x32_bf16 v[78:81], v[162:165], v[242:245], v[78:81]
	v_mfma_f32_16x16x32_bf16 v[70:73], v[176:179], v[242:245], v[70:73]
	v_mfma_f32_16x16x32_bf16 v[126:129], v[166:169], v[222:225], v[126:129]
	v_mfma_f32_16x16x32_bf16 v[118:121], v[180:183], v[222:225], v[118:121]
	v_mfma_f32_16x16x32_bf16 v[110:113], v[166:169], v[230:233], v[110:113]
	v_mfma_f32_16x16x32_bf16 v[102:105], v[180:183], v[230:233], v[102:105]
	v_mfma_f32_16x16x32_bf16 v[94:97], v[166:169], v[238:241], v[94:97]
	v_mfma_f32_16x16x32_bf16 v[86:89], v[180:183], v[238:241], v[86:89]
	v_mfma_f32_16x16x32_bf16 v[78:81], v[166:169], v[246:249], v[78:81]
	v_mfma_f32_16x16x32_bf16 v[70:73], v[180:183], v[246:249], v[70:73]
	s_setprio 0
	s_setprio 1
	v_mfma_f32_16x16x32_bf16 v[122:125], v[184:187], v[208:211], v[122:125]
	v_mfma_f32_16x16x32_bf16 v[114:117], v[192:195], v[208:211], v[114:117]
	v_mfma_f32_16x16x32_bf16 v[106:109], v[184:187], v[226:229], v[106:109]
	v_mfma_f32_16x16x32_bf16 v[98:101], v[192:195], v[226:229], v[98:101]
	v_mfma_f32_16x16x32_bf16 v[90:93], v[184:187], v[234:237], v[90:93]
	v_mfma_f32_16x16x32_bf16 v[82:85], v[192:195], v[234:237], v[82:85]
	v_mfma_f32_16x16x32_bf16 v[74:77], v[184:187], v[242:245], v[74:77]
	v_mfma_f32_16x16x32_bf16 v[66:69], v[192:195], v[242:245], v[66:69]
	v_mfma_f32_16x16x32_bf16 v[122:125], v[188:191], v[222:225], v[122:125]
	v_mfma_f32_16x16x32_bf16 v[114:117], v[196:199], v[222:225], v[114:117]
	v_mfma_f32_16x16x32_bf16 v[106:109], v[188:191], v[230:233], v[106:109]
	v_mfma_f32_16x16x32_bf16 v[98:101], v[196:199], v[230:233], v[98:101]
	v_mfma_f32_16x16x32_bf16 v[90:93], v[188:191], v[238:241], v[90:93]
	v_mfma_f32_16x16x32_bf16 v[82:85], v[196:199], v[238:241], v[82:85]
	v_mfma_f32_16x16x32_bf16 v[74:77], v[188:191], v[246:249], v[74:77]
	v_mfma_f32_16x16x32_bf16 v[66:69], v[196:199], v[246:249], v[66:69]
	s_setprio 0
	s_barrier
	s_add_i32 s24, s60, s36
	s_mov_b32 m0, s24
	ds_read_b128 v[208:211], v161 offset:49152
	ds_read_b128 v[222:225], v161 offset:50176
	ds_read_b128 v[226:229], v161 offset:51200
	ds_read_b128 v[230:233], v161 offset:52224
	ds_read_b128 v[234:237], v161 offset:53248
	ds_read_b128 v[238:241], v161 offset:54272
	ds_read_b128 v[242:245], v161 offset:55296
	ds_read_b128 v[246:249], v161 offset:56320
	global_load_lds_dwordx4 v136, s[98:99]
	s_add_i32 m0, s24, 0x2000
	s_add_u32 s16, s16, 0x80080
	s_addc_u32 s17, s17, 0
	s_add_i32 s24, s61, s36
	global_load_lds_dwordx4 v132, s[98:99]
	s_mov_b32 m0, s24
	s_nop 0
	global_load_lds_dwordx4 v136, s[16:17]
	s_add_i32 m0, s24, 0x2000
	s_nop 0
	global_load_lds_dwordx4 v132, s[16:17]
	s_mov_b32 m0, s45
	s_nop 0
	global_load_lds_dwordx4 v138, s[100:101]
	s_mov_b32 m0, s46
	s_nop 0
	global_load_lds_dwordx4 v134, s[100:101]
	s_waitcnt vmcnt(8)
	s_waitcnt lgkmcnt(0)
	s_barrier
	s_setprio 1
	s_waitcnt lgkmcnt(0)
	v_mfma_f32_16x16x32_bf16 v[62:65], v[162:165], v[208:211], v[62:65]
	v_mfma_f32_16x16x32_bf16 v[54:57], v[176:179], v[208:211], v[54:57]
	v_mfma_f32_16x16x32_bf16 v[46:49], v[162:165], v[226:229], v[46:49]
	v_mfma_f32_16x16x32_bf16 v[38:41], v[176:179], v[226:229], v[38:41]
	v_mfma_f32_16x16x32_bf16 v[30:33], v[162:165], v[234:237], v[30:33]
	v_mfma_f32_16x16x32_bf16 v[22:25], v[176:179], v[234:237], v[22:25]
	v_mfma_f32_16x16x32_bf16 v[14:17], v[162:165], v[242:245], v[14:17]
	v_mfma_f32_16x16x32_bf16 v[6:9], v[176:179], v[242:245], v[6:9]
	v_mfma_f32_16x16x32_bf16 v[62:65], v[166:169], v[222:225], v[62:65]
	v_mfma_f32_16x16x32_bf16 v[54:57], v[180:183], v[222:225], v[54:57]
	v_mfma_f32_16x16x32_bf16 v[46:49], v[166:169], v[230:233], v[46:49]
	v_mfma_f32_16x16x32_bf16 v[38:41], v[180:183], v[230:233], v[38:41]
	v_mfma_f32_16x16x32_bf16 v[30:33], v[166:169], v[238:241], v[30:33]
	v_mfma_f32_16x16x32_bf16 v[22:25], v[180:183], v[238:241], v[22:25]
	v_mfma_f32_16x16x32_bf16 v[14:17], v[166:169], v[246:249], v[14:17]
	v_mfma_f32_16x16x32_bf16 v[6:9], v[180:183], v[246:249], v[6:9]
	s_setprio 0
	s_setprio 1
	v_mfma_f32_16x16x32_bf16 v[58:61], v[184:187], v[208:211], v[58:61]
	v_mfma_f32_16x16x32_bf16 v[50:53], v[192:195], v[208:211], v[50:53]
	v_mfma_f32_16x16x32_bf16 v[42:45], v[184:187], v[226:229], v[42:45]
	v_mfma_f32_16x16x32_bf16 v[34:37], v[192:195], v[226:229], v[34:37]
	v_mfma_f32_16x16x32_bf16 v[26:29], v[184:187], v[234:237], v[26:29]
	v_mfma_f32_16x16x32_bf16 v[18:21], v[192:195], v[234:237], v[18:21]
	v_mfma_f32_16x16x32_bf16 v[10:13], v[184:187], v[242:245], v[10:13]
	v_mfma_f32_16x16x32_bf16 v[2:5], v[192:195], v[242:245], v[2:5]
	v_mfma_f32_16x16x32_bf16 v[58:61], v[188:191], v[222:225], v[58:61]
	v_mfma_f32_16x16x32_bf16 v[50:53], v[196:199], v[222:225], v[50:53]
	v_mfma_f32_16x16x32_bf16 v[42:45], v[188:191], v[230:233], v[42:45]
	v_mfma_f32_16x16x32_bf16 v[34:37], v[196:199], v[230:233], v[34:37]
	v_mfma_f32_16x16x32_bf16 v[26:29], v[188:191], v[238:241], v[26:29]
	v_mfma_f32_16x16x32_bf16 v[18:21], v[196:199], v[238:241], v[18:21]
	v_mfma_f32_16x16x32_bf16 v[10:13], v[188:191], v[246:249], v[10:13]
	v_mfma_f32_16x16x32_bf16 v[2:5], v[196:199], v[246:249], v[2:5]
	s_setprio 0
	s_barrier
	s_add_i32 s59, s59, 2
	s_add_u32 s57, s57, 0x100
	s_addc_u32 s58, s58, 0
	s_add_u32 s14, s14, 0x100
	s_addc_u32 s15, s15, 0
	s_cmp_gt_u32 s59, 29
	s_cbranch_scc0 .LBB0_1188
	s_and_b64 vcc, exec, s[4:5]
	s_cbranch_vccz .LBB0_1191
	s_barrier
